# small (128x128) GEMM K-loops: waves 0-3 sleep 3 after each stage barrier so the two waves of a SIMD alternate LDS-read and MFMA segments
# speedup vs baseline: 1.0009x; 1.0009x over previous
; #define PG8_LAS __attribute__((address_space(3)))
;     ...
;         GS_STAGE(0, cA, cB); GS_STAGE(1, cA + 128, cB + 128); GS_STAGE(2, cA + 256, cB + 256);
;         for (int t = 0; t < nt; ++t) {
;             asm volatile("s_waitcnt vmcnt(8)" ::: "memory"); __builtin_amdgcn_s_barrier();
;             { const int tn = (t + 3 < nt) ? t + 3 : t + 3 - nt; GS_STAGE((t + 3) & 3, cA + (size_t)tn * 128, cB + (size_t)tn * 128); }
;             const int so = (t & 3) * 32768;
;             bf16x8 At[4][2], Bf[2][2];
; #pragma unroll
;             for (int m = 0; m < 4; ++m)
; #pragma unroll
;                 for (int k = 0; k < 2; ++k) At[m][k] = *(const PG8_LAS bf16x8*)(lds + so + aoff + m * 2048 + k * 1024);
; #pragma unroll
;             for (int n = 0; n < 2; ++n)
; #pragma unroll
;                 for (int k = 0; k < 2; ++k) Bf[n][k] = *(const PG8_LAS bf16x8*)(lds + so + 16384 + boff + n * 2048 + k * 1024);
;             asm volatile("s_waitcnt lgkmcnt(0)" ::: "memory"); __builtin_amdgcn_sched_barrier(0);
; #pragma unroll
;             for (int m = 0; m < 4; ++m)
; #pragma unroll
;                 for (int n = 0; n < 2; ++n)
; #pragma unroll
;                     for (int k = 0; k < 2; ++k) acc[m][n] = __builtin_amdgcn_mfma_f32_16x16x32_bf16(Bf[n][k], At[m][k], acc[m][n], 0, 0, 0);
;         }
;         asm volatile("s_waitcnt vmcnt(0)" ::: "memory"); __builtin_amdgcn_s_barrier();
.LBB0_352:
	s_cmp_lt_u32 s46, 29
	s_cselect_b32 s47, 3, 0xffffffe3
	s_add_i32 s48, s46, s47
	s_ashr_i32 s49, s48, 31
	s_lshl_b64 s[48:49], s[48:49], 7
	s_add_u32 s50, s0, s48
	s_addc_u32 s51, s1, s49
	s_add_i32 s47, s45, 0x18000
	s_and_b32 s47, s47, 0x18000
	s_add_i32 s47, s27, s47
	s_add_u32 s48, s22, s48
	s_addc_u32 s49, s23, s49
	s_add_i32 s52, s47, 0x4000
	v_lshl_add_u64 v[34:35], s[50:51], 0, v[128:129]
	s_mov_b32 m0, s47
	s_waitcnt vmcnt(8)
	s_barrier
	v_readfirstlane_b32 s98, v183
	s_cmpk_ge_u32 s98, 0x100
	s_cbranch_scc1 .Lsgs_0
	s_sleep 3
.Lsgs_0:
	global_load_lds_dwordx4 v[34:35], off
	v_lshl_add_u64 v[34:35], s[48:49], 0, v[130:131]
	s_mov_b32 m0, s52
	s_nop 0
	global_load_lds_dwordx4 v[34:35], off
	v_lshl_add_u64 v[34:35], s[50:51], 0, v[132:133]
	s_add_i32 m0, s47, 0x2000
	s_nop 0
	global_load_lds_dwordx4 v[34:35], off
	v_lshl_add_u64 v[34:35], s[48:49], 0, v[134:135]
	s_add_i32 m0, s47, 0x6000
	s_and_b32 s47, s45, 0x10000
	global_load_lds_dwordx4 v[34:35], off
	v_add_u32_e32 v32, s47, v37
	ds_read_b128 v[44:47], v32
	ds_read_b128 v[48:51], v32 offset:1024
	ds_read_b128 v[52:55], v32 offset:2048
	ds_read_b128 v[56:59], v32 offset:3072
	ds_read_b128 v[60:63], v32 offset:4096
	ds_read_b128 v[64:67], v32 offset:5120
	ds_read_b128 v[68:71], v32 offset:6144
	ds_read_b128 v[72:75], v32 offset:7168
	v_add_u32_e32 v32, s47, v39
	ds_read_b128 v[76:79], v32 offset:16384
	ds_read_b128 v[80:83], v32 offset:17408
	ds_read_b128 v[84:87], v32 offset:18432
	ds_read_b128 v[88:91], v32 offset:19456
	s_waitcnt lgkmcnt(0)
	s_add_i32 s47, s46, 1
	s_cmp_lt_u32 s47, 29
	s_cselect_b32 s47, 4, 0xffffffe4
	s_add_i32 s48, s46, s47
	s_ashr_i32 s49, s48, 31
	s_lshl_b64 s[48:49], s[48:49], 7
	s_add_u32 s50, s0, s48
	s_addc_u32 s51, s1, s49
	s_add_i32 s47, s45, 0x20000
	s_and_b32 s47, s47, 0x10000
	s_add_i32 s47, s27, s47
	s_add_u32 s48, s22, s48
	s_addc_u32 s49, s23, s49
	s_add_i32 s52, s47, 0x4000
	v_lshl_add_u64 v[34:35], s[50:51], 0, v[128:129]
	s_mov_b32 m0, s47
	s_waitcnt vmcnt(8)
	s_barrier
	v_readfirstlane_b32 s98, v183
	s_cmpk_ge_u32 s98, 0x100
	s_cbranch_scc1 .Lsgs_1
	s_sleep 3
.Lsgs_1:
	global_load_lds_dwordx4 v[34:35], off
	v_lshl_add_u64 v[34:35], s[48:49], 0, v[130:131]
	s_mov_b32 m0, s52
	s_waitcnt lgkmcnt(0)
	v_mfma_f32_16x16x32_bf16 v[28:31], v[76:79], v[44:47], v[28:31]
	global_load_lds_dwordx4 v[34:35], off
	v_lshl_add_u64 v[34:35], s[50:51], 0, v[132:133]
	s_add_i32 m0, s47, 0x2000
	v_mfma_f32_16x16x32_bf16 v[24:27], v[84:87], v[44:47], v[24:27]
	global_load_lds_dwordx4 v[34:35], off
	v_lshl_add_u64 v[34:35], s[48:49], 0, v[134:135]
	s_add_i32 m0, s47, 0x6000
	v_mfma_f32_16x16x32_bf16 v[20:23], v[76:79], v[52:55], v[20:23]
	global_load_lds_dwordx4 v[34:35], off
	s_add_i32 s47, s45, 0x8000
	v_mfma_f32_16x16x32_bf16 v[16:19], v[84:87], v[52:55], v[16:19]
	s_and_b32 s47, s47, 0x18000
	v_add_u32_e32 v32, s47, v37
	v_mfma_f32_16x16x32_bf16 v[12:15], v[76:79], v[60:63], v[12:15]
	v_mfma_f32_16x16x32_bf16 v[8:11], v[84:87], v[60:63], v[8:11]
	v_mfma_f32_16x16x32_bf16 v[0:3], v[76:79], v[68:71], v[0:3]
	v_mfma_f32_16x16x32_bf16 v[4:7], v[84:87], v[68:71], v[4:7]
	v_mfma_f32_16x16x32_bf16 v[28:31], v[80:83], v[48:51], v[28:31]
	v_mfma_f32_16x16x32_bf16 v[24:27], v[88:91], v[48:51], v[24:27]
	v_mfma_f32_16x16x32_bf16 v[20:23], v[80:83], v[56:59], v[20:23]
	v_mfma_f32_16x16x32_bf16 v[16:19], v[88:91], v[56:59], v[16:19]
	ds_read_b128 v[44:47], v32
	ds_read_b128 v[48:51], v32 offset:1024
	ds_read_b128 v[52:55], v32 offset:2048
	ds_read_b128 v[56:59], v32 offset:3072
	v_mfma_f32_16x16x32_bf16 v[12:15], v[80:83], v[64:67], v[12:15]
	v_mfma_f32_16x16x32_bf16 v[8:11], v[88:91], v[64:67], v[8:11]
	v_mfma_f32_16x16x32_bf16 v[0:3], v[80:83], v[72:75], v[0:3]
	ds_read_b128 v[60:63], v32 offset:4096
	ds_read_b128 v[64:67], v32 offset:5120
	ds_read_b128 v[76:79], v32 offset:6144
	ds_read_b128 v[80:83], v32 offset:7168
	v_add_u32_e32 v32, s47, v39
	ds_read_b128 v[68:71], v32 offset:16384
	ds_read_b128 v[84:87], v32 offset:17408
	v_mfma_f32_16x16x32_bf16 v[4:7], v[88:91], v[72:75], v[4:7]
	ds_read_b128 v[72:75], v32 offset:18432
	ds_read_b128 v[88:91], v32 offset:19456
	s_waitcnt lgkmcnt(0)
	s_waitcnt lgkmcnt(0)
	v_mfma_f32_16x16x32_bf16 v[28:31], v[68:71], v[44:47], v[28:31]
	s_add_i32 s45, s45, 0x10000
	s_add_i32 s46, s46, 2
	s_cmp_eq_u32 s46, 32
	v_mfma_f32_16x16x32_bf16 v[24:27], v[72:75], v[44:47], v[24:27]
	v_mfma_f32_16x16x32_bf16 v[20:23], v[68:71], v[52:55], v[20:23]
	v_mfma_f32_16x16x32_bf16 v[16:19], v[72:75], v[52:55], v[16:19]
	v_mfma_f32_16x16x32_bf16 v[12:15], v[68:71], v[60:63], v[12:15]
	v_mfma_f32_16x16x32_bf16 v[8:11], v[72:75], v[60:63], v[8:11]
	v_mfma_f32_16x16x32_bf16 v[0:3], v[68:71], v[76:79], v[0:3]
	v_mfma_f32_16x16x32_bf16 v[4:7], v[72:75], v[76:79], v[4:7]
	v_mfma_f32_16x16x32_bf16 v[28:31], v[84:87], v[48:51], v[28:31]
	v_mfma_f32_16x16x32_bf16 v[24:27], v[88:91], v[48:51], v[24:27]
	v_mfma_f32_16x16x32_bf16 v[20:23], v[84:87], v[56:59], v[20:23]
	v_mfma_f32_16x16x32_bf16 v[16:19], v[88:91], v[56:59], v[16:19]
	v_mfma_f32_16x16x32_bf16 v[12:15], v[84:87], v[64:67], v[12:15]
	v_mfma_f32_16x16x32_bf16 v[8:11], v[88:91], v[64:67], v[8:11]
	v_mfma_f32_16x16x32_bf16 v[0:3], v[84:87], v[80:83], v[0:3]
	v_mfma_f32_16x16x32_bf16 v[4:7], v[88:91], v[80:83], v[4:7]
	s_cbranch_scc0 .LBB0_352
	s_waitcnt vmcnt(0)
	s_lshr_b32 s45, s25, 2
	s_cmp_lt_i32 s45, 5
	s_mov_b64 s[22:23], -1
	s_barrier
	s_cbranch_scc1 .LBB0_360
	s_cmp_lt_i32 s45, 6
	s_cbranch_scc1 .LBB0_357
	s_mov_b64 s[22:23], 0
	s_cmp_eq_u32 s45, 6
	s_mov_b64 s[0:1], 0
	s_cbranch_scc0 .LBB0_357
	s_mov_b64 s[0:1], s[2:3]

; #define PG8_LAS __attribute__((address_space(3)))
;     ...
;         for (int t = 0; t < nt; ++t) {
;             asm volatile("s_waitcnt vmcnt(8)" ::: "memory"); __builtin_amdgcn_s_barrier();
;             { const int tn = (t + 3 < nt) ? t + 3 : t + 3 - nt; GS_STAGE((t + 3) & 3, cA + (size_t)tn * 128, cB + (size_t)tn * 128); }
;             const int so = (t & 3) * 32768;
;             bf16x8 At[4][2], Bf[2][2];
; #pragma unroll
;             for (int m = 0; m < 4; ++m)
; #pragma unroll
;                 for (int k = 0; k < 2; ++k) At[m][k] = *(const PG8_LAS bf16x8*)(lds + so + aoff + m * 2048 + k * 1024);
; #pragma unroll
;             for (int n = 0; n < 2; ++n)
; #pragma unroll
;                 for (int k = 0; k < 2; ++k) Bf[n][k] = *(const PG8_LAS bf16x8*)(lds + so + 16384 + boff + n * 2048 + k * 1024);
;             asm volatile("s_waitcnt lgkmcnt(0)" ::: "memory"); __builtin_amdgcn_sched_barrier(0);
; #pragma unroll
;             for (int m = 0; m < 4; ++m)
; #pragma unroll
;                 for (int n = 0; n < 2; ++n)
; #pragma unroll
;                     for (int k = 0; k < 2; ++k) acc[m][n] = __builtin_amdgcn_mfma_f32_16x16x32_bf16(Bf[n][k], At[m][k], acc[m][n], 0, 0, 0);
;         }
.LBB0_996:
	s_cmp_lt_u32 s34, 29
	s_cselect_b32 s35, 3, 0xffffffe3
	s_add_i32 s36, s34, s35
	s_ashr_i32 s37, s36, 31
	s_lshl_b64 s[36:37], s[36:37], 7
	s_add_u32 s42, s0, s36
	s_addc_u32 s43, s1, s37
	s_add_i32 s35, s31, 0x18000
	s_and_b32 s35, s35, 0x18000
	s_add_i32 s35, s17, s35
	s_add_u32 s36, s12, s36
	s_addc_u32 s37, s13, s37
	s_add_i32 s41, s35, 0x4000
	v_lshl_add_u64 v[34:35], s[42:43], 0, v[128:129]
	s_mov_b32 m0, s35
	s_waitcnt vmcnt(8)
	s_barrier
	v_readfirstlane_b32 s98, v183
	s_cmpk_ge_u32 s98, 0x100
	s_cbranch_scc1 .Lsgs_2
	s_sleep 3
.Lsgs_2:
	global_load_lds_dwordx4 v[34:35], off
	v_lshl_add_u64 v[34:35], s[36:37], 0, v[128:129]
	s_mov_b32 m0, s41
	s_nop 0
	global_load_lds_dwordx4 v[34:35], off
	v_lshl_add_u64 v[34:35], s[42:43], 0, v[130:131]
	s_add_i32 m0, s35, 0x2000
	s_nop 0
	global_load_lds_dwordx4 v[34:35], off
	v_lshl_add_u64 v[34:35], s[36:37], 0, v[130:131]
	s_add_i32 m0, s35, 0x6000
	s_and_b32 s35, s31, 0x10000
	global_load_lds_dwordx4 v[34:35], off
	v_add_u32_e32 v32, s35, v39
	ds_read_b128 v[34:37], v32
	ds_read_b128 v[44:47], v32 offset:1024
	ds_read_b128 v[48:51], v32 offset:2048
	ds_read_b128 v[52:55], v32 offset:3072
	ds_read_b128 v[56:59], v32 offset:4096
	ds_read_b128 v[60:63], v32 offset:5120
	ds_read_b128 v[64:67], v32 offset:6144
	ds_read_b128 v[68:71], v32 offset:7168
	v_add_u32_e32 v32, s35, v41
	ds_read_b128 v[72:75], v32 offset:16384
	ds_read_b128 v[76:79], v32 offset:17408
	ds_read_b128 v[80:83], v32 offset:18432
	ds_read_b128 v[84:87], v32 offset:19456
	s_waitcnt lgkmcnt(0)
	s_add_i32 s35, s34, 1
	s_cmp_lt_u32 s35, 29
	s_cselect_b32 s35, 4, 0xffffffe4
	s_add_i32 s36, s34, s35
	s_ashr_i32 s37, s36, 31
	s_lshl_b64 s[36:37], s[36:37], 7
	s_add_u32 s42, s0, s36
	s_addc_u32 s43, s1, s37
	s_add_i32 s35, s31, 0x20000
	s_and_b32 s35, s35, 0x10000
	s_add_i32 s35, s17, s35
	s_add_u32 s36, s12, s36
	s_waitcnt lgkmcnt(0)
	v_mfma_f32_16x16x32_bf16 v[28:31], v[72:75], v[34:37], v[28:31]
	s_addc_u32 s37, s13, s37
	s_add_i32 s41, s35, 0x4000
	s_mov_b32 m0, s35
	v_mfma_f32_16x16x32_bf16 v[24:27], v[80:83], v[34:37], v[24:27]
	v_lshl_add_u64 v[34:35], s[42:43], 0, v[128:129]
	s_waitcnt vmcnt(8)
	s_barrier
	v_readfirstlane_b32 s98, v183
	s_cmpk_ge_u32 s98, 0x100
	s_cbranch_scc1 .Lsgs_3
	s_sleep 3
.Lsgs_3:
	global_load_lds_dwordx4 v[34:35], off
	v_lshl_add_u64 v[34:35], s[36:37], 0, v[128:129]
	s_mov_b32 m0, s41
	v_mfma_f32_16x16x32_bf16 v[20:23], v[72:75], v[48:51], v[20:23]
	global_load_lds_dwordx4 v[34:35], off
	v_lshl_add_u64 v[34:35], s[42:43], 0, v[130:131]
	s_add_i32 m0, s35, 0x2000
	v_mfma_f32_16x16x32_bf16 v[16:19], v[80:83], v[48:51], v[16:19]
	global_load_lds_dwordx4 v[34:35], off
	v_lshl_add_u64 v[34:35], s[36:37], 0, v[130:131]
	s_add_i32 m0, s35, 0x6000
	v_mfma_f32_16x16x32_bf16 v[12:15], v[72:75], v[56:59], v[12:15]
	global_load_lds_dwordx4 v[34:35], off
	s_add_i32 s35, s31, 0x8000
	v_mfma_f32_16x16x32_bf16 v[8:11], v[80:83], v[56:59], v[8:11]
	s_and_b32 s35, s35, 0x18000
	v_add_u32_e32 v32, s35, v39
	v_mfma_f32_16x16x32_bf16 v[4:7], v[72:75], v[64:67], v[4:7]
	v_mfma_f32_16x16x32_bf16 v[0:3], v[80:83], v[64:67], v[0:3]
	v_mfma_f32_16x16x32_bf16 v[28:31], v[76:79], v[44:47], v[28:31]
	v_mfma_f32_16x16x32_bf16 v[24:27], v[84:87], v[44:47], v[24:27]
	v_mfma_f32_16x16x32_bf16 v[20:23], v[76:79], v[52:55], v[20:23]
	v_mfma_f32_16x16x32_bf16 v[16:19], v[84:87], v[52:55], v[16:19]
	ds_read_b128 v[34:37], v32
	ds_read_b128 v[44:47], v32 offset:1024
	ds_read_b128 v[48:51], v32 offset:2048
	ds_read_b128 v[52:55], v32 offset:3072
	v_mfma_f32_16x16x32_bf16 v[12:15], v[76:79], v[60:63], v[12:15]
	v_mfma_f32_16x16x32_bf16 v[8:11], v[84:87], v[60:63], v[8:11]
	v_mfma_f32_16x16x32_bf16 v[4:7], v[76:79], v[68:71], v[4:7]
	ds_read_b128 v[56:59], v32 offset:4096
	ds_read_b128 v[60:63], v32 offset:5120
	ds_read_b128 v[72:75], v32 offset:6144
	ds_read_b128 v[76:79], v32 offset:7168
	v_add_u32_e32 v32, s35, v41
	ds_read_b128 v[64:67], v32 offset:16384
	ds_read_b128 v[80:83], v32 offset:17408
	v_mfma_f32_16x16x32_bf16 v[0:3], v[84:87], v[68:71], v[0:3]
	ds_read_b128 v[68:71], v32 offset:18432
	ds_read_b128 v[84:87], v32 offset:19456
	s_waitcnt lgkmcnt(0)
	s_waitcnt lgkmcnt(0)
	v_mfma_f32_16x16x32_bf16 v[28:31], v[64:67], v[34:37], v[28:31]
	s_add_i32 s31, s31, 0x10000
	s_add_i32 s34, s34, 2
	s_cmp_eq_u32 s34, 32
	v_mfma_f32_16x16x32_bf16 v[24:27], v[68:71], v[34:37], v[24:27]
	v_mfma_f32_16x16x32_bf16 v[20:23], v[64:67], v[48:51], v[20:23]
	v_mfma_f32_16x16x32_bf16 v[16:19], v[68:71], v[48:51], v[16:19]
	v_mfma_f32_16x16x32_bf16 v[12:15], v[64:67], v[56:59], v[12:15]
	v_mfma_f32_16x16x32_bf16 v[8:11], v[68:71], v[56:59], v[8:11]
	v_mfma_f32_16x16x32_bf16 v[4:7], v[64:67], v[72:75], v[4:7]
	v_mfma_f32_16x16x32_bf16 v[0:3], v[68:71], v[72:75], v[0:3]
	v_mfma_f32_16x16x32_bf16 v[28:31], v[80:83], v[44:47], v[28:31]
	v_mfma_f32_16x16x32_bf16 v[24:27], v[84:87], v[44:47], v[24:27]
	v_mfma_f32_16x16x32_bf16 v[20:23], v[80:83], v[52:55], v[20:23]
	v_mfma_f32_16x16x32_bf16 v[16:19], v[84:87], v[52:55], v[16:19]
	v_mfma_f32_16x16x32_bf16 v[12:15], v[80:83], v[60:63], v[12:15]
	v_mfma_f32_16x16x32_bf16 v[8:11], v[84:87], v[60:63], v[8:11]
	v_mfma_f32_16x16x32_bf16 v[4:7], v[80:83], v[76:79], v[4:7]
	v_mfma_f32_16x16x32_bf16 v[0:3], v[84:87], v[76:79], v[0:3]
	s_cbranch_scc0 .LBB0_996
; __device__ __forceinline__ unsigned cvtpk(float lo, float hi) { unsigned r; asm volatile("v_cvt_pk_bf16_f32 %0, %1, %2" : "=v"(r) : "v"(lo), "v"(hi)); return r; }
;     __device__ __forceinline__ void quad(const f32x4 (&a)[4][2], int rowq, int colq, int wr, int wc, int fr, int fq) const {
;         const int col0 = colq + wc * 32 + 4 * fq;
; #pragma unroll
;         for (int m = 0; m < 4; ++m) { const int row = rowq + wr * 64 + m * 16 + fr;
;             const float* xr = row < MP ? xp + (size_t)row * DM : xs + (size_t)(row - MP) * DM; float s = 0.f;
; #pragma unroll
;             for (int n = 0; n < 2; ++n) { const int c = col0 + n * 16; f32x4 hv = a[m][n]; if (!pre) hv += *(const f32x4*)(xr + c);
;                 __builtin_nontemporal_store(hv, (f32x4*)(H1 + (size_t)row * DM + c)); s += (hv[0] * hv[0] + hv[1] * hv[1]) + (hv[2] * hv[2] + hv[3] * hv[3]);
;                 const f32x4 gv = *(const f32x4*)(g1 + c); u32x2 w; w.x = cvtpk(hv[0] * gv[0], hv[1] * gv[1]); w.y = cvtpk(hv[2] * gv[2], hv[3] * gv[3]);
;                 *(u32x2*)(A1 + (size_t)row * DM + c) = w; }
;             s += __shfl_xor(s, 16); s += __shfl_xor(s, 32);
;             if (fq == 0) unsafeAtomicAdd(ssq + row, s); }
	v_add_u32_e32 v34, s30, v38
	v_add_u32_e32 v32, 0xffffe000, v34
	v_readlane_b32 s44, v253, 16
	v_lshl_or_b32 v43, s29, 7, v40
	v_lshlrev_b64 v[36:37], 13, v[32:33]
	v_readlane_b32 s46, v253, 18
	v_readlane_b32 s47, v253, 19
	s_waitcnt vmcnt(0)
	s_barrier
	v_mov_b32_e32 v35, v33
	v_lshl_add_u64 v[44:45], s[46:47], 0, v[36:37]
	v_lshlrev_b32_e32 v36, 2, v43
	v_mov_b32_e32 v37, v33
	v_lshl_add_u64 v[52:53], v[44:45], 0, v[36:37]
	global_load_dwordx4 v[44:47], v[52:53], off
	v_readlane_b32 s100, v253, 38
	v_readlane_b32 s101, v253, 39
	s_mov_b32 s98, 0x20000
	s_mov_b32 s99, 0
	global_load_dwordx4 v[100:103], v[52:53], off offset:64
	v_lshl_add_u64 v[88:89], v[52:53], 0, s[98:99]
	global_load_dwordx4 v[104:107], v[88:89], off
	global_load_dwordx4 v[108:111], v[88:89], off offset:64
	v_lshl_add_u64 v[88:89], v[88:89], 0, s[98:99]
	global_load_dwordx4 v[112:115], v[88:89], off
	global_load_dwordx4 v[116:119], v[88:89], off offset:64
	v_lshl_add_u64 v[88:89], v[88:89], 0, s[98:99]
	global_load_dwordx4 v[120:123], v[88:89], off
	global_load_dwordx4 v[124:127], v[88:89], off offset:64
	global_load_dwordx4 v[132:135], v36, s[100:101]
	global_load_dwordx4 v[136:139], v36, s[100:101] offset:64
	v_lshlrev_b64 v[48:49], 13, v[34:35]
	v_readlane_b32 s45, v253, 17
	v_readlane_b32 s48, v253, 20
	v_readlane_b32 s49, v253, 21
	v_readlane_b32 s50, v253, 22
	v_readlane_b32 s51, v253, 23
	v_readlane_b32 s52, v253, 24
	v_readlane_b32 s53, v253, 25
	v_readlane_b32 s54, v253, 26
	v_readlane_b32 s55, v253, 27
	v_readlane_b32 s56, v253, 28
	v_readlane_b32 s57, v253, 29
	v_readlane_b32 s58, v253, 30
	v_readlane_b32 s59, v253, 31
	v_lshl_add_u64 v[48:49], s[6:7], 0, v[48:49]
	v_lshl_add_u64 v[54:55], v[48:49], 0, v[36:37]
	v_readlane_b32 s44, v253, 32
	v_readlane_b32 s50, v253, 38
	v_readlane_b32 s51, v253, 39
	v_readlane_b32 s45, v253, 33
	v_readlane_b32 s46, v253, 34
	v_readlane_b32 s47, v253, 35
	v_readlane_b32 s48, v253, 36
	v_readlane_b32 s49, v253, 37
	v_readlane_b32 s52, v253, 40
	v_readlane_b32 s53, v253, 41
	v_readlane_b32 s54, v253, 42
	v_readlane_b32 s55, v253, 43
	v_readlane_b32 s56, v253, 44
	v_readlane_b32 s57, v253, 45
	v_readlane_b32 s58, v253, 46
	v_readlane_b32 s59, v253, 47
	s_waitcnt vmcnt(0)
	v_pk_add_f32 v[46:47], v[30:31], v[46:47]
	v_pk_add_f32 v[44:45], v[28:29], v[44:45]
	global_store_dwordx4 v[54:55], v[44:47], off nt
	v_lshlrev_b64 v[30:31], 12, v[34:35]
	v_mov_b32_e32 v29, v33
	v_lshlrev_b32_e32 v28, 1, v43
	v_lshl_add_u64 v[30:31], s[8:9], 0, v[30:31]
	v_lshl_add_u64 v[30:31], v[30:31], 0, v[28:29]
	v_mov_b32_e32 v48, v132
	v_mov_b32_e32 v49, v133
	v_mov_b32_e32 v50, v134
	v_mov_b32_e32 v51, v135
	v_mul_f32_e32 v43, v45, v49
	v_mul_f32_e32 v49, v46, v50
	v_mul_f32_e32 v32, v44, v48
	v_mul_f32_e32 v50, v47, v51
	v_cvt_pk_bf16_f32 v48, v32, v43
	v_cvt_pk_bf16_f32 v49, v49, v50
	global_store_dwordx2 v[30:31], v[48:49], off
	v_mov_b32_e32 v48, v100
	v_mov_b32_e32 v49, v101
	v_mov_b32_e32 v50, v102
	v_mov_b32_e32 v51, v103
	v_pk_add_f32 v[50:51], v[26:27], v[50:51]
	v_pk_add_f32 v[48:49], v[24:25], v[48:49]
	global_store_dwordx4 v[54:55], v[48:51], off offset:64 nt
	v_and_b32_e32 v25, 64, v42
	v_xor_b32_e32 v24, 16, v42
	v_add_u32_e32 v25, 64, v25
	v_cmp_lt_i32_e64 s[0:1], v24, v25
	v_mul_f32_e32 v27, v47, v47
	v_fmac_f32_e32 v27, v46, v46
	v_cndmask_b32_e64 v24, v42, v24, s[0:1]
	v_lshlrev_b32_e32 v26, 2, v24
	v_mul_f32_e32 v24, v45, v45
	v_fmac_f32_e32 v24, v44, v44
	v_add_f32_e32 v24, v24, v27
	v_mul_f32_e32 v27, v49, v49
	v_mul_f32_e32 v32, v51, v51
	v_fmac_f32_e32 v27, v48, v48
	v_fmac_f32_e32 v32, v50, v50
	v_add_f32_e32 v27, v27, v32
	v_add_f32_e32 v24, v24, v27
	ds_bpermute_b32 v32, v26, v24
	v_xor_b32_e32 v27, 32, v42
	v_cmp_lt_i32_e64 s[0:1], v27, v25
	s_waitcnt lgkmcnt(0)
	v_add_f32_e32 v24, v24, v32
	v_cndmask_b32_e64 v25, v42, v27, s[0:1]
	v_lshlrev_b32_e32 v27, 2, v25
	ds_bpermute_b32 v25, v27, v24
	v_mov_b32_e32 v52, v136
	v_mov_b32_e32 v53, v137
	v_mov_b32_e32 v54, v138
	v_mov_b32_e32 v55, v139
	v_mul_f32_e32 v45, v50, v54
	v_mul_f32_e32 v32, v48, v52
	v_mul_f32_e32 v43, v49, v53
	v_mul_f32_e32 v46, v51, v55
	v_cvt_pk_bf16_f32 v44, v32, v43
	v_cvt_pk_bf16_f32 v45, v45, v46
	global_store_dwordx2 v[30:31], v[44:45], off offset:32
	s_and_saveexec_b64 s[0:1], vcc
	s_cbranch_execz .LBB0_999
	v_lshl_add_u64 v[30:31], v[34:35], 2, s[92:93]
	s_waitcnt lgkmcnt(0)
	v_add_f32_e32 v24, v24, v25
	global_atomic_add_f32 v[30:31], v24, off

; #define PG8_LAS __attribute__((address_space(3)))
;     ...
;         for (int t = 0; t < nt; ++t) {
;             asm volatile("s_waitcnt vmcnt(8)" ::: "memory"); __builtin_amdgcn_s_barrier();
;             { const int tn = (t + 3 < nt) ? t + 3 : t + 3 - nt; GS_STAGE((t + 3) & 3, cA + (size_t)tn * 128, cB + (size_t)tn * 128); }
;             const int so = (t & 3) * 32768;
;             bf16x8 At[4][2], Bf[2][2];
; #pragma unroll
;             for (int m = 0; m < 4; ++m)
; #pragma unroll
;                 for (int k = 0; k < 2; ++k) At[m][k] = *(const PG8_LAS bf16x8*)(lds + so + aoff + m * 2048 + k * 1024);
; #pragma unroll
;             for (int n = 0; n < 2; ++n)
; #pragma unroll
;                 for (int k = 0; k < 2; ++k) Bf[n][k] = *(const PG8_LAS bf16x8*)(lds + so + 16384 + boff + n * 2048 + k * 1024);
;             asm volatile("s_waitcnt lgkmcnt(0)" ::: "memory"); __builtin_amdgcn_sched_barrier(0);
; #pragma unroll
;             for (int m = 0; m < 4; ++m)
; #pragma unroll
;                 for (int n = 0; n < 2; ++n)
; #pragma unroll
;                     for (int k = 0; k < 2; ++k) acc[m][n] = __builtin_amdgcn_mfma_f32_16x16x32_bf16(Bf[n][k], At[m][k], acc[m][n], 0, 0, 0);
;         }
.LBB0_1103:
	s_cmp_lt_u32 s45, 29
	s_cselect_b32 s46, 3, 0xffffffe3
	s_add_i32 s46, s45, s46
	s_ashr_i32 s47, s46, 31
	s_lshl_b64 s[46:47], s[46:47], 7
	s_add_u32 s48, s16, s46
	s_addc_u32 s49, s17, s47
	s_add_i32 s50, s44, 0x18000
	s_and_b32 s50, s50, 0x18000
	s_add_i32 s50, s23, s50
	s_add_u32 s46, s18, s46
	s_addc_u32 s47, s19, s47
	s_add_i32 s51, s50, 0x4000
	v_lshl_add_u64 v[34:35], s[48:49], 0, v[128:129]
	s_mov_b32 m0, s50
	s_waitcnt vmcnt(8)
	s_barrier
	v_readfirstlane_b32 s98, v183
	s_cmpk_ge_u32 s98, 0x100
	s_cbranch_scc1 .Lsgs_4
	s_sleep 3
.Lsgs_4:
	global_load_lds_dwordx4 v[34:35], off
	v_lshl_add_u64 v[34:35], s[46:47], 0, v[130:131]
	s_mov_b32 m0, s51
	s_nop 0
	global_load_lds_dwordx4 v[34:35], off
	v_lshl_add_u64 v[34:35], s[48:49], 0, v[132:133]
	s_add_i32 m0, s50, 0x2000
	s_nop 0
	global_load_lds_dwordx4 v[34:35], off
	v_lshl_add_u64 v[34:35], s[46:47], 0, v[134:135]
	s_add_i32 m0, s50, 0x6000
	s_and_b32 s46, s44, 0x10000
	global_load_lds_dwordx4 v[34:35], off
	v_add_u32_e32 v32, s46, v40
	ds_read_b128 v[34:37], v32
	s_waitcnt lgkmcnt(0)
	ds_read_b128 v[44:47], v32 offset:1024
	ds_read_b128 v[48:51], v32 offset:2048
	ds_read_b128 v[52:55], v32 offset:3072
	ds_read_b128 v[56:59], v32 offset:4096
	ds_read_b128 v[60:63], v32 offset:5120
	ds_read_b128 v[64:67], v32 offset:6144
	ds_read_b128 v[68:71], v32 offset:7168
	v_add_u32_e32 v32, s46, v41
	ds_read_b128 v[72:75], v32 offset:16384
	ds_read_b128 v[76:79], v32 offset:17408
	ds_read_b128 v[80:83], v32 offset:18432
	ds_read_b128 v[84:87], v32 offset:19456
	s_waitcnt lgkmcnt(0)
	s_add_i32 s46, s45, 1
	s_cmp_lt_u32 s46, 29
	s_cselect_b32 s46, 4, 0xffffffe4
	s_add_i32 s46, s45, s46
	s_ashr_i32 s47, s46, 31
	s_lshl_b64 s[46:47], s[46:47], 7
	s_add_u32 s48, s16, s46
	s_addc_u32 s49, s17, s47
	s_add_i32 s50, s44, 0x20000
	s_and_b32 s50, s50, 0x10000
	s_add_i32 s50, s23, s50
	s_add_u32 s46, s18, s46
	s_waitcnt lgkmcnt(0)
	v_mfma_f32_16x16x32_bf16 v[28:31], v[72:75], v[34:37], v[28:31]
	s_addc_u32 s47, s19, s47
	s_add_i32 s51, s50, 0x4000
	s_mov_b32 m0, s50
	v_mfma_f32_16x16x32_bf16 v[24:27], v[80:83], v[34:37], v[24:27]
	v_lshl_add_u64 v[34:35], s[48:49], 0, v[128:129]
	s_waitcnt vmcnt(8)
	s_barrier
	v_readfirstlane_b32 s98, v183
	s_cmpk_ge_u32 s98, 0x100
	s_cbranch_scc1 .Lsgs_5
	s_sleep 3
;     __device__ __forceinline__ void quad(const f32x4 (&a)[4][2], int rowq, int colq, int wr, int wc, int fr, int fq) const {
;         const int row0 = rowq + wr * 64 + fr, col0 = colq + wc * 32 + 8 * fq;
;         if (colq < 2 * CW) {
; #pragma unroll
;             for (int m = 0; m < 4; ++m) { const int row = row0 + m * 16; const float rs = rsqrtf(ssq1[row] * (1.f / DM) + RMS_EPS);
;                 const f32x4 uu = a[m][0] * rs, zz = a[m][1] * rs; u32x2 w;
;                 w.x = cvtpk(uu[0] * silu_fast(zz[0]), uu[1] * silu_fast(zz[1])); w.y = cvtpk(uu[2] * silu_fast(zz[2]), uu[3] * silu_fast(zz[3]));
;                 const int cu = col0 >> 1; *(u32x2*)(UZV + ((size_t)(cu >> 8) * MT + row) * 256 + (cu & 255)) = w; }
;         } else {
; #pragma unroll
;             for (int m = 0; m < 4; ++m) { const int row = row0 + m * 16; const float rs = rsqrtf(ssq1[row] * (1.f / DM) + RMS_EPS);
;                 const f32x4 v0 = a[m][0] * rs, v1 = a[m][1] * rs;
;                 u32x4 w; w.x = cvtpk(v0[0], v0[1]); w.y = cvtpk(v0[2], v0[3]); w.z = cvtpk(v1[0], v1[1]); w.w = cvtpk(v1[2], v1[3]);
;     ...
;         for (int t = 0; t < nt; ++t) {
;             asm volatile("s_waitcnt vmcnt(8)" ::: "memory"); __builtin_amdgcn_s_barrier();
;             { const int tn = (t + 3 < nt) ? t + 3 : t + 3 - nt; GS_STAGE((t + 3) & 3, cA + (size_t)tn * 128, cB + (size_t)tn * 128); }
;             const int so = (t & 3) * 32768;
;             bf16x8 At[4][2], Bf[2][2];
; #pragma unroll
;             for (int m = 0; m < 4; ++m)
; #pragma unroll
;                 for (int k = 0; k < 2; ++k) At[m][k] = *(const PG8_LAS bf16x8*)(lds + so + aoff + m * 2048 + k * 1024);
; #pragma unroll
;             for (int n = 0; n < 2; ++n)
; #pragma unroll
;                 for (int k = 0; k < 2; ++k) Bf[n][k] = *(const PG8_LAS bf16x8*)(lds + so + 16384 + boff + n * 2048 + k * 1024);
;             asm volatile("s_waitcnt lgkmcnt(0)" ::: "memory"); __builtin_amdgcn_sched_barrier(0);
; #pragma unroll
;             for (int m = 0; m < 4; ++m)
; #pragma unroll
;                 for (int n = 0; n < 2; ++n)
; #pragma unroll
;                     for (int k = 0; k < 2; ++k) acc[m][n] = __builtin_amdgcn_mfma_f32_16x16x32_bf16(Bf[n][k], At[m][k], acc[m][n], 0, 0, 0);
;         }
;         asm volatile("s_waitcnt vmcnt(0)" ::: "memory"); __builtin_amdgcn_s_barrier();
.Lsgs_5:
	global_load_lds_dwordx4 v[34:35], off
	v_lshl_add_u64 v[34:35], s[46:47], 0, v[130:131]
	s_mov_b32 m0, s51
	v_mfma_f32_16x16x32_bf16 v[20:23], v[72:75], v[48:51], v[20:23]
	global_load_lds_dwordx4 v[34:35], off
	v_lshl_add_u64 v[34:35], s[48:49], 0, v[132:133]
	s_add_i32 m0, s50, 0x2000
	v_mfma_f32_16x16x32_bf16 v[16:19], v[80:83], v[48:51], v[16:19]
	global_load_lds_dwordx4 v[34:35], off
	v_lshl_add_u64 v[34:35], s[46:47], 0, v[134:135]
	s_add_i32 m0, s50, 0x6000
	v_mfma_f32_16x16x32_bf16 v[12:15], v[72:75], v[56:59], v[12:15]
	global_load_lds_dwordx4 v[34:35], off
	s_add_i32 s46, s44, 0x8000
	v_mfma_f32_16x16x32_bf16 v[8:11], v[80:83], v[56:59], v[8:11]
	s_and_b32 s46, s46, 0x18000
	v_add_u32_e32 v32, s46, v40
	v_mfma_f32_16x16x32_bf16 v[0:3], v[72:75], v[64:67], v[0:3]
	v_mfma_f32_16x16x32_bf16 v[4:7], v[80:83], v[64:67], v[4:7]
	v_mfma_f32_16x16x32_bf16 v[28:31], v[76:79], v[44:47], v[28:31]
	v_mfma_f32_16x16x32_bf16 v[24:27], v[84:87], v[44:47], v[24:27]
	v_mfma_f32_16x16x32_bf16 v[20:23], v[76:79], v[52:55], v[20:23]
	v_mfma_f32_16x16x32_bf16 v[16:19], v[84:87], v[52:55], v[16:19]
	ds_read_b128 v[34:37], v32
	ds_read_b128 v[44:47], v32 offset:1024
	ds_read_b128 v[48:51], v32 offset:2048
	ds_read_b128 v[52:55], v32 offset:3072
	v_mfma_f32_16x16x32_bf16 v[12:15], v[76:79], v[60:63], v[12:15]
	v_mfma_f32_16x16x32_bf16 v[8:11], v[84:87], v[60:63], v[8:11]
	v_mfma_f32_16x16x32_bf16 v[0:3], v[76:79], v[68:71], v[0:3]
	ds_read_b128 v[56:59], v32 offset:4096
	ds_read_b128 v[60:63], v32 offset:5120
	ds_read_b128 v[72:75], v32 offset:6144
	ds_read_b128 v[76:79], v32 offset:7168
	v_add_u32_e32 v32, s46, v41
	ds_read_b128 v[64:67], v32 offset:16384
	ds_read_b128 v[80:83], v32 offset:17408
	v_mfma_f32_16x16x32_bf16 v[4:7], v[84:87], v[68:71], v[4:7]
	ds_read_b128 v[68:71], v32 offset:18432
	ds_read_b128 v[84:87], v32 offset:19456
	s_waitcnt lgkmcnt(0)
	s_waitcnt lgkmcnt(0)
	v_mfma_f32_16x16x32_bf16 v[28:31], v[64:67], v[34:37], v[28:31]
	s_add_i32 s44, s44, 0x10000
	s_add_i32 s45, s45, 2
	s_cmp_eq_u32 s45, 32
	v_mfma_f32_16x16x32_bf16 v[24:27], v[68:71], v[34:37], v[24:27]
	v_mfma_f32_16x16x32_bf16 v[20:23], v[64:67], v[48:51], v[20:23]
	v_mfma_f32_16x16x32_bf16 v[16:19], v[68:71], v[48:51], v[16:19]
	v_mfma_f32_16x16x32_bf16 v[12:15], v[64:67], v[56:59], v[12:15]
	v_mfma_f32_16x16x32_bf16 v[8:11], v[68:71], v[56:59], v[8:11]
	v_mfma_f32_16x16x32_bf16 v[0:3], v[64:67], v[72:75], v[0:3]
	v_mfma_f32_16x16x32_bf16 v[4:7], v[68:71], v[72:75], v[4:7]
	v_mfma_f32_16x16x32_bf16 v[28:31], v[80:83], v[44:47], v[28:31]
	v_mfma_f32_16x16x32_bf16 v[24:27], v[84:87], v[44:47], v[24:27]
	v_mfma_f32_16x16x32_bf16 v[20:23], v[80:83], v[52:55], v[20:23]
	v_mfma_f32_16x16x32_bf16 v[16:19], v[84:87], v[52:55], v[16:19]
	v_mfma_f32_16x16x32_bf16 v[12:15], v[80:83], v[60:63], v[12:15]
	v_mfma_f32_16x16x32_bf16 v[8:11], v[84:87], v[60:63], v[8:11]
	v_mfma_f32_16x16x32_bf16 v[0:3], v[80:83], v[76:79], v[0:3]
	v_mfma_f32_16x16x32_bf16 v[4:7], v[84:87], v[76:79], v[4:7]
	s_cbranch_scc0 .LBB0_1103
	v_add_u32_e32 v34, s43, v39
	v_mov_b32_e32 v35, v33
	v_lshl_add_u64 v[36:37], v[34:35], 2, s[92:93]
	s_waitcnt vmcnt(0)
	s_barrier
	global_load_dword v32, v[36:37], off
	global_load_dword v240, v[36:37], off offset:64
	global_load_dword v241, v[36:37], off offset:128
	global_load_dword v242, v[36:37], off offset:192
	s_lshl_b32 s18, s37, 7
	v_or_b32_e32 v44, s18, v38
	s_cmp_lt_u32 s42, 64
	s_mov_b64 s[16:17], -1
	s_waitcnt vmcnt(0)
	v_fmamk_f32 v32, v32, 0x3a000000, v42
	v_mul_f32_e32 v36, 0x4b800000, v32
	v_cmp_gt_f32_e32 vcc, s36, v32
	s_nop 1
	v_cndmask_b32_e32 v32, v32, v36, vcc
	v_rsq_f32_e32 v32, v32
	s_nop 0
	v_mul_f32_e32 v36, 0x45800000, v32
	v_cndmask_b32_e32 v32, v32, v36, vcc
	v_pk_mul_f32 v[30:31], v[30:31], v[32:33] op_sel_hi:[1,0]
	v_pk_mul_f32 v[28:29], v[28:29], v[32:33] op_sel_hi:[1,0]
	v_pk_mul_f32 v[26:27], v[26:27], v[32:33] op_sel_hi:[1,0]
	v_pk_mul_f32 v[24:25], v[24:25], v[32:33] op_sel_hi:[1,0]
	s_cbranch_scc1 .LBB0_1114
	s_addk_i32 s18, 0xe000
	s_lshr_b32 s16, s18, 8
	s_mulk_i32 s16, 0x2200
	s_ashr_i32 s17, s16, 31
	v_lshl_add_u64 v[36:37], s[16:17], 0, v[34:35]
	v_lshlrev_b64 v[36:37], 9, v[36:37]
	v_lshl_add_u64 v[54:55], s[2:3], 0, v[36:37]
	v_add_f32_e32 v32, v28, v29
	v_add_f32_e32 v36, v30, v31
	v_add_f32_e32 v32, v32, v36
	v_add_f32_e32 v36, v24, v25
	v_add_f32_e32 v37, v26, v27
	v_add_f32_e32 v36, v36, v37
	v_add_f32_e32 v32, v32, v36
	v_mul_f32_e32 v36, v29, v29
	v_mul_f32_e32 v37, v31, v31
	v_fmac_f32_e32 v36, v28, v28
	v_fmac_f32_e32 v37, v30, v30
	v_and_b32_e32 v46, 64, v43
	v_add_f32_e32 v36, v36, v37
	v_mul_f32_e32 v37, v25, v25
	v_xor_b32_e32 v45, 16, v43
	v_add_u32_e32 v46, 64, v46
	v_mul_f32_e32 v48, v27, v27
	v_fmac_f32_e32 v37, v24, v24
	v_cmp_lt_i32_e32 vcc, v45, v46
	v_fmac_f32_e32 v48, v26, v26
	v_add_f32_e32 v37, v37, v48
	v_cndmask_b32_e32 v45, v43, v45, vcc
	v_lshlrev_b32_e32 v45, 2, v45
	v_add_f32_e32 v36, v36, v37
	ds_bpermute_b32 v47, v45, v32
	ds_bpermute_b32 v48, v45, v36
	v_xor_b32_e32 v37, 32, v43
	v_cmp_lt_i32_e32 vcc, v37, v46
	v_and_b32_e32 v56, 0xf8, v44
	s_waitcnt lgkmcnt(1)
	v_add_f32_e32 v32, v32, v47
	v_cndmask_b32_e32 v37, v43, v37, vcc
	v_lshlrev_b32_e32 v46, 2, v37
	s_waitcnt lgkmcnt(0)
	v_add_f32_e32 v48, v36, v48
	ds_bpermute_b32 v47, v46, v32
	ds_bpermute_b32 v49, v46, v48
	v_lshlrev_b32_e32 v36, 1, v56
	v_mov_b32_e32 v37, v33
	v_lshl_add_u64 v[54:55], v[54:55], 0, v[36:37]
	v_cvt_pk_bf16_f32 v50, v28, v29
	v_cvt_pk_bf16_f32 v51, v30, v31
	v_cvt_pk_bf16_f32 v52, v24, v25
	v_cvt_pk_bf16_f32 v53, v26, v27
	global_store_dwordx4 v[54:55], v[50:53], off
	s_and_saveexec_b64 s[18:19], s[0:1]
	s_cbranch_execz .LBB0_1107
	v_lshlrev_b64 v[50:51], 2, v[34:35]
	v_lshl_add_u64 v[52:53], s[10:11], 0, v[50:51]
	v_lshl_add_u64 v[50:51], s[8:9], 0, v[50:51]
	s_waitcnt lgkmcnt(1)
	v_add_f32_e32 v32, v32, v47
	s_waitcnt lgkmcnt(0)
	v_add_f32_e32 v35, v48, v49
	global_atomic_add_f32 v[50:51], v32, off
	global_atomic_add_f32 v[52:53], v35, off

; #define PG8_LAS __attribute__((address_space(3)))
;     ...
;         const char* cA = (const char*)A + ((size_t)(row_off + pm * 128) * K + (size_t)split * (K / KS)) * 2; const char* cB = (const char*)Bt + ((size_t)(pn * 128) * K + (size_t)split * (K / KS)) * 2;
;         f32x4 acc[4][2];
; #pragma unroll
;         for (int m = 0; m < 4; ++m) { acc[m][0] = (f32x4){0.f, 0.f, 0.f, 0.f}; acc[m][1] = (f32x4){0.f, 0.f, 0.f, 0.f}; }
;         GS_STAGE(0, cA, cB); GS_STAGE(1, cA + 128, cB + 128); GS_STAGE(2, cA + 256, cB + 256);
;         for (int t = 0; t < nt; ++t) {
;             asm volatile("s_waitcnt vmcnt(8)" ::: "memory"); __builtin_amdgcn_s_barrier();
;             { const int tn = (t + 3 < nt) ? t + 3 : t + 3 - nt; GS_STAGE((t + 3) & 3, cA + (size_t)tn * 128, cB + (size_t)tn * 128); }
;             const int so = (t & 3) * 32768;
;             bf16x8 At[4][2], Bf[2][2];
; #pragma unroll
;             for (int m = 0; m < 4; ++m)
; #pragma unroll
;                 for (int k = 0; k < 2; ++k) At[m][k] = *(const PG8_LAS bf16x8*)(lds + so + aoff + m * 2048 + k * 1024);
; #pragma unroll
;             for (int n = 0; n < 2; ++n)
; #pragma unroll
;                 for (int k = 0; k < 2; ++k) Bf[n][k] = *(const PG8_LAS bf16x8*)(lds + so + 16384 + boff + n * 2048 + k * 1024);
;             asm volatile("s_waitcnt lgkmcnt(0)" ::: "memory"); __builtin_amdgcn_sched_barrier(0);
; #pragma unroll
;             for (int m = 0; m < 4; ++m)
; #pragma unroll
;                 for (int n = 0; n < 2; ++n)
; #pragma unroll
;                     for (int k = 0; k < 2; ++k) acc[m][n] = __builtin_amdgcn_mfma_f32_16x16x32_bf16(Bf[n][k], At[m][k], acc[m][n], 0, 0, 0);
;         }
.LBB0_1385:
	s_cmp_gt_u32 s54, 31
	s_mov_b32 s12, 5
	s_cbranch_scc1 .LBB0_1405
	s_lshr_b32 s2, s54, 1
	s_bfe_u32 s3, s54, 0x20002
	s_and_b32 s2, s2, 8
	s_lshl_b32 s81, s3, 7
	s_or_b32 s80, s2, s55
	s_and_b32 s2, s54, 3
	s_bitset1_b32 s81, 13
	s_lshl_b32 s12, s2, 11
	s_lshl_b32 s46, s81, 13
	s_or_b32 s46, s46, s12
	s_add_u32 s46, s50, s46
	s_addc_u32 s47, s51, 0
	s_lshl_b32 s48, s80, 20
	s_or_b32 s12, s48, s12
	s_add_u32 s48, s52, s12
	s_mov_b32 m0, s57
	s_addc_u32 s49, s53, 0
	v_lshl_add_u64 v[22:23], s[46:47], 0, v[128:129]
	global_load_lds_dwordx4 v[22:23], off
	v_lshl_add_u64 v[20:21], s[48:49], 0, v[128:129]
	s_mov_b32 m0, s59
	v_lshl_add_u64 v[18:19], s[46:47], 0, v[130:131]
	global_load_lds_dwordx4 v[20:21], off
	s_mov_b32 m0, s60
	v_lshl_add_u64 v[16:17], s[48:49], 0, v[130:131]
	global_load_lds_dwordx4 v[18:19], off
	s_mov_b32 m0, s62
	v_lshl_add_u64 v[14:15], v[22:23], 0, s[14:15]
	global_load_lds_dwordx4 v[16:17], off
	s_mov_b32 m0, s64
	v_lshl_add_u64 v[12:13], v[20:21], 0, s[14:15]
	global_load_lds_dwordx4 v[14:15], off
	s_mov_b32 m0, s66
	v_lshl_add_u64 v[10:11], v[18:19], 0, s[14:15]
	global_load_lds_dwordx4 v[12:13], off
	s_mov_b32 m0, s68
	v_lshl_add_u64 v[8:9], v[16:17], 0, s[14:15]
	global_load_lds_dwordx4 v[10:11], off
	s_mov_b32 m0, s70
	v_lshl_add_u64 v[6:7], v[22:23], 0, s[16:17]
	global_load_lds_dwordx4 v[8:9], off
	s_mov_b32 m0, s71
	s_waitcnt lgkmcnt(0)
	v_lshl_add_u64 v[4:5], v[20:21], 0, s[16:17]
	global_load_lds_dwordx4 v[6:7], off
	s_mov_b32 m0, s72
	v_lshl_add_u64 v[2:3], v[18:19], 0, s[16:17]
	global_load_lds_dwordx4 v[4:5], off
	s_mov_b32 m0, s73
	v_lshl_add_u64 v[0:1], v[16:17], 0, s[16:17]
	global_load_lds_dwordx4 v[2:3], off
	s_mov_b32 m0, s74
	v_lshl_add_u64 v[24:25], v[22:23], 0, s[18:19]
	global_load_lds_dwordx4 v[0:1], off
	s_mov_b32 m0, s75
	s_waitcnt vmcnt(8)
	s_barrier
	global_load_lds_dwordx4 v[24:25], off
	v_lshl_add_u64 v[24:25], v[20:21], 0, s[18:19]
	s_mov_b32 m0, s76
	s_nop 0
	global_load_lds_dwordx4 v[24:25], off
	v_lshl_add_u64 v[24:25], v[18:19], 0, s[18:19]
	s_mov_b32 m0, s77
	s_nop 0
	global_load_lds_dwordx4 v[24:25], off
	v_lshl_add_u64 v[24:25], v[16:17], 0, s[18:19]
	s_mov_b32 m0, s78
	s_nop 0
	global_load_lds_dwordx4 v[24:25], off
	ds_read_b128 v[24:27], v43
	ds_read_b128 v[28:31], v43 offset:1024
	ds_read_b128 v[36:39], v43 offset:2048
	ds_read_b128 v[66:69], v43 offset:3072
	ds_read_b128 v[70:73], v43 offset:4096
	ds_read_b128 v[74:77], v43 offset:5120
	ds_read_b128 v[78:81], v43 offset:6144
	ds_read_b128 v[82:85], v43 offset:7168
	ds_read_b128 v[86:89], v61 offset:16384
	ds_read_b128 v[90:93], v61 offset:17408
	ds_read_b128 v[94:97], v61 offset:18432
	ds_read_b128 v[98:101], v61 offset:19456
	s_waitcnt lgkmcnt(0)
	s_mov_b32 m0, s57
	v_lshl_add_u64 v[40:41], v[22:23], 0, s[20:21]
	s_waitcnt vmcnt(8)
	s_barrier
	global_load_lds_dwordx4 v[40:41], off
	v_lshl_add_u64 v[40:41], v[20:21], 0, s[20:21]
	s_mov_b32 m0, s59
	s_waitcnt lgkmcnt(0)
	v_mfma_f32_16x16x32_bf16 v[102:105], v[86:89], v[24:27], 0
	global_load_lds_dwordx4 v[40:41], off
	v_lshl_add_u64 v[40:41], v[18:19], 0, s[20:21]
	s_mov_b32 m0, s60
	v_mfma_f32_16x16x32_bf16 v[24:27], v[94:97], v[24:27], 0
	global_load_lds_dwordx4 v[40:41], off
	v_lshl_add_u64 v[40:41], v[16:17], 0, s[20:21]
	s_mov_b32 m0, s62
	v_mfma_f32_16x16x32_bf16 v[102:105], v[90:93], v[28:31], v[102:105]
	global_load_lds_dwordx4 v[40:41], off
	v_mfma_f32_16x16x32_bf16 v[24:27], v[98:101], v[28:31], v[24:27]
	v_mfma_f32_16x16x32_bf16 v[28:31], v[86:89], v[36:39], 0
	v_mfma_f32_16x16x32_bf16 v[36:39], v[94:97], v[36:39], 0
	v_mfma_f32_16x16x32_bf16 v[28:31], v[90:93], v[66:69], v[28:31]
	v_mfma_f32_16x16x32_bf16 v[36:39], v[98:101], v[66:69], v[36:39]
	v_mfma_f32_16x16x32_bf16 v[66:69], v[86:89], v[70:73], 0
	v_mfma_f32_16x16x32_bf16 v[70:73], v[94:97], v[70:73], 0
	v_mfma_f32_16x16x32_bf16 v[66:69], v[90:93], v[74:77], v[66:69]
	v_mfma_f32_16x16x32_bf16 v[70:73], v[98:101], v[74:77], v[70:73]
	v_mfma_f32_16x16x32_bf16 v[74:77], v[86:89], v[78:81], 0
	ds_read_b128 v[86:89], v43 offset:32768
	ds_read_b128 v[106:109], v43 offset:33792
	ds_read_b128 v[110:113], v43 offset:34816
	ds_read_b128 v[114:117], v43 offset:35840
	v_mfma_f32_16x16x32_bf16 v[74:77], v[90:93], v[82:85], v[74:77]
	ds_read_b128 v[90:93], v43 offset:36864
	ds_read_b128 v[118:121], v43 offset:37888
	ds_read_b128 v[122:125], v43 offset:38912
	ds_read_b128 v[132:135], v43 offset:39936
	v_mfma_f32_16x16x32_bf16 v[78:81], v[94:97], v[78:81], 0
	ds_read_b128 v[94:97], v61 offset:49152
	ds_read_b128 v[136:139], v61 offset:50176
	ds_read_b128 v[140:143], v61 offset:51200
	ds_read_b128 v[144:147], v61 offset:52224
	s_waitcnt lgkmcnt(0)
	v_mfma_f32_16x16x32_bf16 v[78:81], v[98:101], v[82:85], v[78:81]
	s_mov_b32 m0, s64
	v_lshl_add_u64 v[40:41], v[22:23], 0, s[22:23]
	s_waitcnt vmcnt(8)
	s_barrier
; #define PG8_LAS __attribute__((address_space(3)))
;     ...
;         for (int t = 0; t < nt; ++t) {
;             asm volatile("s_waitcnt vmcnt(8)" ::: "memory"); __builtin_amdgcn_s_barrier();
;             { const int tn = (t + 3 < nt) ? t + 3 : t + 3 - nt; GS_STAGE((t + 3) & 3, cA + (size_t)tn * 128, cB + (size_t)tn * 128); }
;             const int so = (t & 3) * 32768;
;             bf16x8 At[4][2], Bf[2][2];
; #pragma unroll
;             for (int m = 0; m < 4; ++m)
; #pragma unroll
;                 for (int k = 0; k < 2; ++k) At[m][k] = *(const PG8_LAS bf16x8*)(lds + so + aoff + m * 2048 + k * 1024);
; #pragma unroll
;             for (int n = 0; n < 2; ++n)
; #pragma unroll
;                 for (int k = 0; k < 2; ++k) Bf[n][k] = *(const PG8_LAS bf16x8*)(lds + so + 16384 + boff + n * 2048 + k * 1024);
;             asm volatile("s_waitcnt lgkmcnt(0)" ::: "memory"); __builtin_amdgcn_sched_barrier(0);
; #pragma unroll
;             for (int m = 0; m < 4; ++m)
; #pragma unroll
;                 for (int n = 0; n < 2; ++n)
; #pragma unroll
;                     for (int k = 0; k < 2; ++k) acc[m][n] = __builtin_amdgcn_mfma_f32_16x16x32_bf16(Bf[n][k], At[m][k], acc[m][n], 0, 0, 0);
;         }
	global_load_lds_dwordx4 v[40:41], off
	v_lshl_add_u64 v[40:41], v[20:21], 0, s[22:23]
	s_mov_b32 m0, s66
	s_waitcnt lgkmcnt(0)
	v_mfma_f32_16x16x32_bf16 v[82:85], v[94:97], v[86:89], v[102:105]
	global_load_lds_dwordx4 v[40:41], off
	v_lshl_add_u64 v[40:41], v[18:19], 0, s[22:23]
	s_mov_b32 m0, s68
	v_mfma_f32_16x16x32_bf16 v[24:27], v[140:143], v[86:89], v[24:27]
	global_load_lds_dwordx4 v[40:41], off
	v_lshl_add_u64 v[40:41], v[16:17], 0, s[22:23]
	s_mov_b32 m0, s70
	v_mfma_f32_16x16x32_bf16 v[28:31], v[94:97], v[110:113], v[28:31]
	global_load_lds_dwordx4 v[40:41], off
	v_mfma_f32_16x16x32_bf16 v[36:39], v[140:143], v[110:113], v[36:39]
	v_mfma_f32_16x16x32_bf16 v[66:69], v[94:97], v[90:93], v[66:69]
	v_mfma_f32_16x16x32_bf16 v[70:73], v[140:143], v[90:93], v[70:73]
	v_mfma_f32_16x16x32_bf16 v[74:77], v[94:97], v[122:125], v[74:77]
	ds_read_b128 v[86:89], v44
	ds_read_b128 v[90:93], v45
	ds_read_b128 v[94:97], v46
	ds_read_b128 v[98:101], v47
	v_mfma_f32_16x16x32_bf16 v[82:85], v[136:139], v[106:109], v[82:85]
	v_mfma_f32_16x16x32_bf16 v[24:27], v[144:147], v[106:109], v[24:27]
	v_mfma_f32_16x16x32_bf16 v[28:31], v[136:139], v[114:117], v[28:31]
	v_mfma_f32_16x16x32_bf16 v[36:39], v[144:147], v[114:117], v[36:39]
	ds_read_b128 v[102:105], v48
	ds_read_b128 v[106:109], v49
	ds_read_b128 v[110:113], v50
	ds_read_b128 v[114:117], v51
	v_mfma_f32_16x16x32_bf16 v[66:69], v[136:139], v[118:121], v[66:69]
	v_mfma_f32_16x16x32_bf16 v[70:73], v[144:147], v[118:121], v[70:73]
	v_mfma_f32_16x16x32_bf16 v[74:77], v[136:139], v[132:135], v[74:77]
	v_mfma_f32_16x16x32_bf16 v[78:81], v[140:143], v[122:125], v[78:81]
	ds_read_b128 v[118:121], v62
	ds_read_b128 v[122:125], v62 offset:1024
	ds_read_b128 v[136:139], v62 offset:2048
	ds_read_b128 v[140:143], v62 offset:3072
	s_waitcnt lgkmcnt(0)
	v_mfma_f32_16x16x32_bf16 v[78:81], v[144:147], v[132:135], v[78:81]
	s_mov_b32 m0, s71
	v_lshl_add_u64 v[40:41], v[22:23], 0, s[24:25]
	s_waitcnt vmcnt(8)
	s_barrier
	global_load_lds_dwordx4 v[40:41], off
	v_lshl_add_u64 v[40:41], v[20:21], 0, s[24:25]
	s_mov_b32 m0, s72
	s_waitcnt lgkmcnt(0)
	v_mfma_f32_16x16x32_bf16 v[82:85], v[118:121], v[86:89], v[82:85]
	global_load_lds_dwordx4 v[40:41], off
	v_lshl_add_u64 v[40:41], v[18:19], 0, s[24:25]
	s_mov_b32 m0, s73
	v_mfma_f32_16x16x32_bf16 v[24:27], v[136:139], v[86:89], v[24:27]
	global_load_lds_dwordx4 v[40:41], off
	v_lshl_add_u64 v[40:41], v[16:17], 0, s[24:25]
	s_mov_b32 m0, s74
	v_mfma_f32_16x16x32_bf16 v[28:31], v[118:121], v[94:97], v[28:31]
	global_load_lds_dwordx4 v[40:41], off
	v_mfma_f32_16x16x32_bf16 v[36:39], v[136:139], v[94:97], v[36:39]
	v_mfma_f32_16x16x32_bf16 v[66:69], v[118:121], v[102:105], v[66:69]
	v_mfma_f32_16x16x32_bf16 v[70:73], v[136:139], v[102:105], v[70:73]
	v_mfma_f32_16x16x32_bf16 v[74:77], v[118:121], v[110:113], v[74:77]
	v_mfma_f32_16x16x32_bf16 v[82:85], v[122:125], v[90:93], v[82:85]
	v_mfma_f32_16x16x32_bf16 v[24:27], v[140:143], v[90:93], v[24:27]
	v_mfma_f32_16x16x32_bf16 v[28:31], v[122:125], v[98:101], v[28:31]
	v_mfma_f32_16x16x32_bf16 v[36:39], v[140:143], v[98:101], v[36:39]
	ds_read_b128 v[86:89], v52
	ds_read_b128 v[90:93], v53
	ds_read_b128 v[94:97], v54
	ds_read_b128 v[98:101], v55
	v_mfma_f32_16x16x32_bf16 v[66:69], v[122:125], v[106:109], v[66:69]
	v_mfma_f32_16x16x32_bf16 v[70:73], v[140:143], v[106:109], v[70:73]
	v_mfma_f32_16x16x32_bf16 v[74:77], v[122:125], v[114:117], v[74:77]
	ds_read_b128 v[102:105], v56
	ds_read_b128 v[106:109], v57
	ds_read_b128 v[118:121], v58
	ds_read_b128 v[122:125], v59
	v_mfma_f32_16x16x32_bf16 v[78:81], v[136:139], v[110:113], v[78:81]
	ds_read_b128 v[110:113], v63
	ds_read_b128 v[132:135], v63 offset:1024
	ds_read_b128 v[136:139], v63 offset:2048
	ds_read_b128 v[144:147], v63 offset:3072
	s_waitcnt lgkmcnt(0)
	v_mfma_f32_16x16x32_bf16 v[78:81], v[140:143], v[114:117], v[78:81]
	s_mov_b32 m0, s75
	v_lshl_add_u64 v[40:41], v[22:23], 0, s[26:27]
	s_waitcnt vmcnt(8)
	s_barrier
	global_load_lds_dwordx4 v[40:41], off
	v_lshl_add_u64 v[40:41], v[20:21], 0, s[26:27]
	s_mov_b32 m0, s76
	s_waitcnt lgkmcnt(0)
	v_mfma_f32_16x16x32_bf16 v[82:85], v[110:113], v[86:89], v[82:85]
	global_load_lds_dwordx4 v[40:41], off
	v_lshl_add_u64 v[40:41], v[18:19], 0, s[26:27]
	s_mov_b32 m0, s77
	v_mfma_f32_16x16x32_bf16 v[24:27], v[136:139], v[86:89], v[24:27]
	global_load_lds_dwordx4 v[40:41], off
	v_lshl_add_u64 v[40:41], v[16:17], 0, s[26:27]
	s_mov_b32 m0, s78
	v_mfma_f32_16x16x32_bf16 v[28:31], v[110:113], v[94:97], v[28:31]
	global_load_lds_dwordx4 v[40:41], off
	v_mfma_f32_16x16x32_bf16 v[36:39], v[136:139], v[94:97], v[36:39]
	v_mfma_f32_16x16x32_bf16 v[66:69], v[110:113], v[102:105], v[66:69]
	v_mfma_f32_16x16x32_bf16 v[70:73], v[136:139], v[102:105], v[70:73]
	v_mfma_f32_16x16x32_bf16 v[74:77], v[110:113], v[118:121], v[74:77]
	v_mfma_f32_16x16x32_bf16 v[82:85], v[132:135], v[90:93], v[82:85]
	v_mfma_f32_16x16x32_bf16 v[24:27], v[144:147], v[90:93], v[24:27]
	v_mfma_f32_16x16x32_bf16 v[28:31], v[132:135], v[98:101], v[28:31]
	v_mfma_f32_16x16x32_bf16 v[36:39], v[144:147], v[98:101], v[36:39]
	ds_read_b128 v[86:89], v43
	ds_read_b128 v[90:93], v43 offset:1024
	ds_read_b128 v[94:97], v43 offset:2048
	ds_read_b128 v[98:101], v43 offset:3072
	v_mfma_f32_16x16x32_bf16 v[66:69], v[132:135], v[106:109], v[66:69]
	v_mfma_f32_16x16x32_bf16 v[70:73], v[144:147], v[106:109], v[70:73]
	ds_read_b128 v[102:105], v43 offset:4096
	ds_read_b128 v[106:109], v43 offset:5120
	ds_read_b128 v[110:113], v43 offset:6144
	ds_read_b128 v[114:117], v43 offset:7168
	v_mfma_f32_16x16x32_bf16 v[74:77], v[132:135], v[122:125], v[74:77]
	v_mfma_f32_16x16x32_bf16 v[78:81], v[136:139], v[118:121], v[78:81]
	ds_read_b128 v[118:121], v61 offset:16384
	ds_read_b128 v[132:135], v61 offset:17408
	ds_read_b128 v[136:139], v61 offset:18432
	ds_read_b128 v[140:143], v61 offset:19456
	s_waitcnt lgkmcnt(0)
	v_mfma_f32_16x16x32_bf16 v[78:81], v[144:147], v[122:125], v[78:81]
	s_mov_b32 m0, s57
	v_lshl_add_u64 v[40:41], v[22:23], 0, s[28:29]
	s_waitcnt vmcnt(8)
	s_barrier
; #define PG8_LAS __attribute__((address_space(3)))
;     ...
;         for (int t = 0; t < nt; ++t) {
;             asm volatile("s_waitcnt vmcnt(8)" ::: "memory"); __builtin_amdgcn_s_barrier();
;             { const int tn = (t + 3 < nt) ? t + 3 : t + 3 - nt; GS_STAGE((t + 3) & 3, cA + (size_t)tn * 128, cB + (size_t)tn * 128); }
;             const int so = (t & 3) * 32768;
;             bf16x8 At[4][2], Bf[2][2];
; #pragma unroll
;             for (int m = 0; m < 4; ++m)
; #pragma unroll
;                 for (int k = 0; k < 2; ++k) At[m][k] = *(const PG8_LAS bf16x8*)(lds + so + aoff + m * 2048 + k * 1024);
; #pragma unroll
;             for (int n = 0; n < 2; ++n)
; #pragma unroll
;                 for (int k = 0; k < 2; ++k) Bf[n][k] = *(const PG8_LAS bf16x8*)(lds + so + 16384 + boff + n * 2048 + k * 1024);
;             asm volatile("s_waitcnt lgkmcnt(0)" ::: "memory"); __builtin_amdgcn_sched_barrier(0);
; #pragma unroll
;             for (int m = 0; m < 4; ++m)
; #pragma unroll
;                 for (int n = 0; n < 2; ++n)
; #pragma unroll
;                     for (int k = 0; k < 2; ++k) acc[m][n] = __builtin_amdgcn_mfma_f32_16x16x32_bf16(Bf[n][k], At[m][k], acc[m][n], 0, 0, 0);
;         }
	global_load_lds_dwordx4 v[40:41], off
	v_lshl_add_u64 v[40:41], v[20:21], 0, s[28:29]
	s_mov_b32 m0, s59
	s_waitcnt lgkmcnt(0)
	v_mfma_f32_16x16x32_bf16 v[82:85], v[118:121], v[86:89], v[82:85]
	global_load_lds_dwordx4 v[40:41], off
	v_lshl_add_u64 v[40:41], v[18:19], 0, s[28:29]
	s_mov_b32 m0, s60
	v_mfma_f32_16x16x32_bf16 v[24:27], v[136:139], v[86:89], v[24:27]
	global_load_lds_dwordx4 v[40:41], off
	v_lshl_add_u64 v[40:41], v[16:17], 0, s[28:29]
	s_mov_b32 m0, s62
	v_mfma_f32_16x16x32_bf16 v[28:31], v[118:121], v[94:97], v[28:31]
	global_load_lds_dwordx4 v[40:41], off
	v_mfma_f32_16x16x32_bf16 v[36:39], v[136:139], v[94:97], v[36:39]
	v_mfma_f32_16x16x32_bf16 v[66:69], v[118:121], v[102:105], v[66:69]
	v_mfma_f32_16x16x32_bf16 v[70:73], v[136:139], v[102:105], v[70:73]
	v_mfma_f32_16x16x32_bf16 v[74:77], v[118:121], v[110:113], v[74:77]
	v_mfma_f32_16x16x32_bf16 v[82:85], v[132:135], v[90:93], v[82:85]
	v_mfma_f32_16x16x32_bf16 v[24:27], v[140:143], v[90:93], v[24:27]
	v_mfma_f32_16x16x32_bf16 v[28:31], v[132:135], v[98:101], v[28:31]
	v_mfma_f32_16x16x32_bf16 v[36:39], v[140:143], v[98:101], v[36:39]
	ds_read_b128 v[86:89], v43 offset:32768
	ds_read_b128 v[90:93], v43 offset:33792
	ds_read_b128 v[94:97], v43 offset:34816
	ds_read_b128 v[98:101], v43 offset:35840
	v_mfma_f32_16x16x32_bf16 v[66:69], v[132:135], v[106:109], v[66:69]
	v_mfma_f32_16x16x32_bf16 v[70:73], v[140:143], v[106:109], v[70:73]
	ds_read_b128 v[102:105], v43 offset:36864
	ds_read_b128 v[106:109], v43 offset:37888
	ds_read_b128 v[118:121], v43 offset:38912
	ds_read_b128 v[122:125], v43 offset:39936
	v_mfma_f32_16x16x32_bf16 v[74:77], v[132:135], v[114:117], v[74:77]
	v_mfma_f32_16x16x32_bf16 v[78:81], v[136:139], v[110:113], v[78:81]
	ds_read_b128 v[110:113], v61 offset:49152
	ds_read_b128 v[132:135], v61 offset:50176
	ds_read_b128 v[136:139], v61 offset:51200
	ds_read_b128 v[144:147], v61 offset:52224
	s_waitcnt lgkmcnt(0)
	v_mfma_f32_16x16x32_bf16 v[78:81], v[140:143], v[114:117], v[78:81]
	s_mov_b32 m0, s64
	v_lshl_add_u64 v[40:41], v[22:23], 0, s[30:31]
	s_waitcnt vmcnt(8)
	s_barrier
	global_load_lds_dwordx4 v[40:41], off
	v_lshl_add_u64 v[40:41], v[20:21], 0, s[30:31]
	s_mov_b32 m0, s66
	s_waitcnt lgkmcnt(0)
	v_mfma_f32_16x16x32_bf16 v[82:85], v[110:113], v[86:89], v[82:85]
	global_load_lds_dwordx4 v[40:41], off
	v_lshl_add_u64 v[40:41], v[18:19], 0, s[30:31]
	s_mov_b32 m0, s68
	v_mfma_f32_16x16x32_bf16 v[24:27], v[136:139], v[86:89], v[24:27]
	global_load_lds_dwordx4 v[40:41], off
	v_lshl_add_u64 v[40:41], v[16:17], 0, s[30:31]
	s_mov_b32 m0, s70
	v_mfma_f32_16x16x32_bf16 v[28:31], v[110:113], v[94:97], v[28:31]
	global_load_lds_dwordx4 v[40:41], off
	v_mfma_f32_16x16x32_bf16 v[36:39], v[136:139], v[94:97], v[36:39]
	v_mfma_f32_16x16x32_bf16 v[66:69], v[110:113], v[102:105], v[66:69]
	v_mfma_f32_16x16x32_bf16 v[70:73], v[136:139], v[102:105], v[70:73]
	v_mfma_f32_16x16x32_bf16 v[74:77], v[110:113], v[118:121], v[74:77]
	v_mfma_f32_16x16x32_bf16 v[82:85], v[132:135], v[90:93], v[82:85]
	v_mfma_f32_16x16x32_bf16 v[24:27], v[144:147], v[90:93], v[24:27]
	v_mfma_f32_16x16x32_bf16 v[28:31], v[132:135], v[98:101], v[28:31]
	v_mfma_f32_16x16x32_bf16 v[36:39], v[144:147], v[98:101], v[36:39]
	ds_read_b128 v[86:89], v44
	ds_read_b128 v[90:93], v45
	ds_read_b128 v[94:97], v46
	ds_read_b128 v[98:101], v47
	v_mfma_f32_16x16x32_bf16 v[66:69], v[132:135], v[106:109], v[66:69]
	v_mfma_f32_16x16x32_bf16 v[70:73], v[144:147], v[106:109], v[70:73]
	ds_read_b128 v[102:105], v48
	ds_read_b128 v[106:109], v49
	ds_read_b128 v[110:113], v50
	ds_read_b128 v[114:117], v51
	v_mfma_f32_16x16x32_bf16 v[74:77], v[132:135], v[122:125], v[74:77]
	v_mfma_f32_16x16x32_bf16 v[78:81], v[136:139], v[118:121], v[78:81]
	ds_read_b128 v[118:121], v62
	ds_read_b128 v[132:135], v62 offset:1024
	ds_read_b128 v[136:139], v62 offset:2048
	ds_read_b128 v[140:143], v62 offset:3072
	s_waitcnt lgkmcnt(0)
	v_mfma_f32_16x16x32_bf16 v[78:81], v[144:147], v[122:125], v[78:81]
	s_mov_b32 m0, s71
	v_lshl_add_u64 v[40:41], v[22:23], 0, s[34:35]
	s_waitcnt vmcnt(8)
	s_barrier
	global_load_lds_dwordx4 v[40:41], off
	v_lshl_add_u64 v[40:41], v[20:21], 0, s[34:35]
	s_mov_b32 m0, s72
	s_waitcnt lgkmcnt(0)
	v_mfma_f32_16x16x32_bf16 v[82:85], v[118:121], v[86:89], v[82:85]
	global_load_lds_dwordx4 v[40:41], off
	v_lshl_add_u64 v[40:41], v[18:19], 0, s[34:35]
	s_mov_b32 m0, s73
	v_mfma_f32_16x16x32_bf16 v[24:27], v[136:139], v[86:89], v[24:27]
	global_load_lds_dwordx4 v[40:41], off
	v_lshl_add_u64 v[40:41], v[16:17], 0, s[34:35]
	s_mov_b32 m0, s74
	v_mfma_f32_16x16x32_bf16 v[28:31], v[118:121], v[94:97], v[28:31]
	global_load_lds_dwordx4 v[40:41], off
	v_mfma_f32_16x16x32_bf16 v[36:39], v[136:139], v[94:97], v[36:39]
	v_mfma_f32_16x16x32_bf16 v[66:69], v[118:121], v[102:105], v[66:69]
	v_mfma_f32_16x16x32_bf16 v[70:73], v[136:139], v[102:105], v[70:73]
	v_mfma_f32_16x16x32_bf16 v[74:77], v[118:121], v[110:113], v[74:77]
	v_mfma_f32_16x16x32_bf16 v[82:85], v[132:135], v[90:93], v[82:85]
	v_mfma_f32_16x16x32_bf16 v[24:27], v[140:143], v[90:93], v[24:27]
	v_mfma_f32_16x16x32_bf16 v[28:31], v[132:135], v[98:101], v[28:31]
	v_mfma_f32_16x16x32_bf16 v[36:39], v[140:143], v[98:101], v[36:39]
	ds_read_b128 v[86:89], v52
	ds_read_b128 v[90:93], v53
	ds_read_b128 v[94:97], v54
	ds_read_b128 v[98:101], v55
	v_mfma_f32_16x16x32_bf16 v[66:69], v[132:135], v[106:109], v[66:69]
	v_mfma_f32_16x16x32_bf16 v[70:73], v[140:143], v[106:109], v[70:73]
	ds_read_b128 v[102:105], v56
	ds_read_b128 v[106:109], v57
	ds_read_b128 v[118:121], v58
	ds_read_b128 v[122:125], v59
	v_mfma_f32_16x16x32_bf16 v[74:77], v[132:135], v[114:117], v[74:77]
	v_mfma_f32_16x16x32_bf16 v[78:81], v[136:139], v[110:113], v[78:81]
	ds_read_b128 v[110:113], v63
	ds_read_b128 v[132:135], v63 offset:1024
	ds_read_b128 v[136:139], v63 offset:2048
	ds_read_b128 v[144:147], v63 offset:3072
	s_waitcnt lgkmcnt(0)
	v_mfma_f32_16x16x32_bf16 v[78:81], v[140:143], v[114:117], v[78:81]
	s_mov_b32 m0, s75
	v_lshl_add_u64 v[40:41], v[22:23], 0, s[36:37]
	s_waitcnt vmcnt(8)
	s_barrier
	v_readfirstlane_b32 s98, v183
	s_cmpk_ge_u32 s98, 0x100
	s_cbranch_scc1 .Lsgs_6
	s_sleep 3
; #define PG8_LAS __attribute__((address_space(3)))
;     ...
;         for (int t = 0; t < nt; ++t) {
;             asm volatile("s_waitcnt vmcnt(8)" ::: "memory"); __builtin_amdgcn_s_barrier();
;             { const int tn = (t + 3 < nt) ? t + 3 : t + 3 - nt; GS_STAGE((t + 3) & 3, cA + (size_t)tn * 128, cB + (size_t)tn * 128); }
;             const int so = (t & 3) * 32768;
;             bf16x8 At[4][2], Bf[2][2];
; #pragma unroll
;             for (int m = 0; m < 4; ++m)
; #pragma unroll
;                 for (int k = 0; k < 2; ++k) At[m][k] = *(const PG8_LAS bf16x8*)(lds + so + aoff + m * 2048 + k * 1024);
; #pragma unroll
;             for (int n = 0; n < 2; ++n)
; #pragma unroll
;                 for (int k = 0; k < 2; ++k) Bf[n][k] = *(const PG8_LAS bf16x8*)(lds + so + 16384 + boff + n * 2048 + k * 1024);
;             asm volatile("s_waitcnt lgkmcnt(0)" ::: "memory"); __builtin_amdgcn_sched_barrier(0);
; #pragma unroll
;             for (int m = 0; m < 4; ++m)
; #pragma unroll
;                 for (int n = 0; n < 2; ++n)
; #pragma unroll
;                     for (int k = 0; k < 2; ++k) acc[m][n] = __builtin_amdgcn_mfma_f32_16x16x32_bf16(Bf[n][k], At[m][k], acc[m][n], 0, 0, 0);
;         }
.Lsgs_6:
	global_load_lds_dwordx4 v[40:41], off
	v_lshl_add_u64 v[40:41], v[20:21], 0, s[36:37]
	s_mov_b32 m0, s76
	s_waitcnt lgkmcnt(0)
	v_mfma_f32_16x16x32_bf16 v[82:85], v[110:113], v[86:89], v[82:85]
	global_load_lds_dwordx4 v[40:41], off
	v_lshl_add_u64 v[40:41], v[18:19], 0, s[36:37]
	s_mov_b32 m0, s77
	v_mfma_f32_16x16x32_bf16 v[24:27], v[136:139], v[86:89], v[24:27]
	global_load_lds_dwordx4 v[40:41], off
	v_lshl_add_u64 v[40:41], v[16:17], 0, s[36:37]
	s_mov_b32 m0, s78
	v_mfma_f32_16x16x32_bf16 v[28:31], v[110:113], v[94:97], v[28:31]
	global_load_lds_dwordx4 v[40:41], off
	v_mfma_f32_16x16x32_bf16 v[36:39], v[136:139], v[94:97], v[36:39]
	v_mfma_f32_16x16x32_bf16 v[66:69], v[110:113], v[102:105], v[66:69]
	v_mfma_f32_16x16x32_bf16 v[70:73], v[136:139], v[102:105], v[70:73]
	v_mfma_f32_16x16x32_bf16 v[74:77], v[110:113], v[118:121], v[74:77]
	v_mfma_f32_16x16x32_bf16 v[82:85], v[132:135], v[90:93], v[82:85]
	v_mfma_f32_16x16x32_bf16 v[24:27], v[144:147], v[90:93], v[24:27]
	v_mfma_f32_16x16x32_bf16 v[28:31], v[132:135], v[98:101], v[28:31]
	v_mfma_f32_16x16x32_bf16 v[36:39], v[144:147], v[98:101], v[36:39]
	ds_read_b128 v[86:89], v43
	ds_read_b128 v[90:93], v43 offset:1024
	ds_read_b128 v[94:97], v43 offset:2048
	ds_read_b128 v[98:101], v43 offset:3072
	v_mfma_f32_16x16x32_bf16 v[66:69], v[132:135], v[106:109], v[66:69]
	v_mfma_f32_16x16x32_bf16 v[70:73], v[144:147], v[106:109], v[70:73]
	ds_read_b128 v[102:105], v43 offset:4096
	ds_read_b128 v[106:109], v43 offset:5120
	ds_read_b128 v[110:113], v43 offset:6144
	ds_read_b128 v[114:117], v43 offset:7168
	v_mfma_f32_16x16x32_bf16 v[74:77], v[132:135], v[122:125], v[74:77]
	v_mfma_f32_16x16x32_bf16 v[78:81], v[136:139], v[118:121], v[78:81]
	ds_read_b128 v[118:121], v61 offset:16384
	ds_read_b128 v[132:135], v61 offset:17408
	ds_read_b128 v[136:139], v61 offset:18432
	ds_read_b128 v[140:143], v61 offset:19456
	s_waitcnt lgkmcnt(0)
	v_mfma_f32_16x16x32_bf16 v[78:81], v[144:147], v[122:125], v[78:81]
	s_mov_b32 m0, s57
	v_lshl_add_u64 v[40:41], v[22:23], 0, s[38:39]
	s_waitcnt vmcnt(8)
	s_barrier
	v_readfirstlane_b32 s98, v183
	s_cmpk_ge_u32 s98, 0x100
	s_cbranch_scc1 .Lsgs_7
	s_sleep 3
.Lsgs_7:
	global_load_lds_dwordx4 v[40:41], off
	v_lshl_add_u64 v[40:41], v[20:21], 0, s[38:39]
	s_mov_b32 m0, s59
	s_waitcnt lgkmcnt(0)
	v_mfma_f32_16x16x32_bf16 v[82:85], v[118:121], v[86:89], v[82:85]
	global_load_lds_dwordx4 v[40:41], off
	v_lshl_add_u64 v[40:41], v[18:19], 0, s[38:39]
	s_mov_b32 m0, s60
	v_mfma_f32_16x16x32_bf16 v[24:27], v[136:139], v[86:89], v[24:27]
	global_load_lds_dwordx4 v[40:41], off
	v_lshl_add_u64 v[40:41], v[16:17], 0, s[38:39]
	s_mov_b32 m0, s62
	v_mfma_f32_16x16x32_bf16 v[28:31], v[118:121], v[94:97], v[28:31]
	global_load_lds_dwordx4 v[40:41], off
	v_mfma_f32_16x16x32_bf16 v[36:39], v[136:139], v[94:97], v[36:39]
	v_mfma_f32_16x16x32_bf16 v[66:69], v[118:121], v[102:105], v[66:69]
	v_mfma_f32_16x16x32_bf16 v[70:73], v[136:139], v[102:105], v[70:73]
	v_mfma_f32_16x16x32_bf16 v[74:77], v[118:121], v[110:113], v[74:77]
	v_mfma_f32_16x16x32_bf16 v[82:85], v[132:135], v[90:93], v[82:85]
	v_mfma_f32_16x16x32_bf16 v[24:27], v[140:143], v[90:93], v[24:27]
	v_mfma_f32_16x16x32_bf16 v[28:31], v[132:135], v[98:101], v[28:31]
	v_mfma_f32_16x16x32_bf16 v[36:39], v[140:143], v[98:101], v[36:39]
	ds_read_b128 v[86:89], v43 offset:32768
	ds_read_b128 v[90:93], v43 offset:33792
	ds_read_b128 v[94:97], v43 offset:34816
	ds_read_b128 v[98:101], v43 offset:35840
	v_mfma_f32_16x16x32_bf16 v[66:69], v[132:135], v[106:109], v[66:69]
	v_mfma_f32_16x16x32_bf16 v[70:73], v[140:143], v[106:109], v[70:73]
	ds_read_b128 v[102:105], v43 offset:36864
	ds_read_b128 v[106:109], v43 offset:37888
	ds_read_b128 v[118:121], v43 offset:38912
	ds_read_b128 v[122:125], v43 offset:39936
	v_mfma_f32_16x16x32_bf16 v[74:77], v[132:135], v[114:117], v[74:77]
	v_mfma_f32_16x16x32_bf16 v[78:81], v[136:139], v[110:113], v[78:81]
	ds_read_b128 v[110:113], v61 offset:49152
	ds_read_b128 v[132:135], v61 offset:50176
	ds_read_b128 v[136:139], v61 offset:51200
	ds_read_b128 v[144:147], v61 offset:52224
	s_waitcnt lgkmcnt(0)
	v_mfma_f32_16x16x32_bf16 v[78:81], v[140:143], v[114:117], v[78:81]
	s_mov_b32 m0, s64
	v_lshl_add_u64 v[40:41], v[22:23], 0, s[40:41]
	s_waitcnt vmcnt(8)
	s_barrier
	v_readfirstlane_b32 s98, v183
	s_cmpk_ge_u32 s98, 0x100
	s_cbranch_scc1 .Lsgs_8
	s_sleep 3
.Lsgs_8:
	global_load_lds_dwordx4 v[40:41], off
	v_lshl_add_u64 v[40:41], v[20:21], 0, s[40:41]
	s_mov_b32 m0, s66
	s_waitcnt lgkmcnt(0)
	v_mfma_f32_16x16x32_bf16 v[82:85], v[110:113], v[86:89], v[82:85]
	global_load_lds_dwordx4 v[40:41], off
	v_lshl_add_u64 v[40:41], v[18:19], 0, s[40:41]
	s_mov_b32 m0, s68
	v_mfma_f32_16x16x32_bf16 v[24:27], v[136:139], v[86:89], v[24:27]
	global_load_lds_dwordx4 v[40:41], off
	v_lshl_add_u64 v[40:41], v[16:17], 0, s[40:41]
	s_mov_b32 m0, s70
	v_mfma_f32_16x16x32_bf16 v[28:31], v[110:113], v[94:97], v[28:31]
	global_load_lds_dwordx4 v[40:41], off
	v_mfma_f32_16x16x32_bf16 v[36:39], v[136:139], v[94:97], v[36:39]
	v_mfma_f32_16x16x32_bf16 v[66:69], v[110:113], v[102:105], v[66:69]
	v_mfma_f32_16x16x32_bf16 v[70:73], v[136:139], v[102:105], v[70:73]
	v_mfma_f32_16x16x32_bf16 v[74:77], v[110:113], v[118:121], v[74:77]
	v_mfma_f32_16x16x32_bf16 v[82:85], v[132:135], v[90:93], v[82:85]
	v_mfma_f32_16x16x32_bf16 v[24:27], v[144:147], v[90:93], v[24:27]
	v_mfma_f32_16x16x32_bf16 v[28:31], v[132:135], v[98:101], v[28:31]
	v_mfma_f32_16x16x32_bf16 v[36:39], v[144:147], v[98:101], v[36:39]
	ds_read_b128 v[86:89], v44
	ds_read_b128 v[90:93], v45
	ds_read_b128 v[94:97], v46
	ds_read_b128 v[98:101], v47
	v_mfma_f32_16x16x32_bf16 v[66:69], v[132:135], v[106:109], v[66:69]
	v_mfma_f32_16x16x32_bf16 v[70:73], v[144:147], v[106:109], v[70:73]
	ds_read_b128 v[102:105], v48
	ds_read_b128 v[106:109], v49
	ds_read_b128 v[110:113], v50
	ds_read_b128 v[114:117], v51
	v_mfma_f32_16x16x32_bf16 v[74:77], v[132:135], v[122:125], v[74:77]
	v_mfma_f32_16x16x32_bf16 v[78:81], v[136:139], v[118:121], v[78:81]
	ds_read_b128 v[118:121], v62
	ds_read_b128 v[132:135], v62 offset:1024
	ds_read_b128 v[136:139], v62 offset:2048
	ds_read_b128 v[140:143], v62 offset:3072
	s_waitcnt lgkmcnt(0)
	v_mfma_f32_16x16x32_bf16 v[78:81], v[144:147], v[122:125], v[78:81]
	s_mov_b32 m0, s71
	v_lshl_add_u64 v[40:41], v[22:23], 0, s[42:43]
	s_waitcnt vmcnt(8)
	s_barrier
	v_readfirstlane_b32 s98, v183
	s_cmpk_ge_u32 s98, 0x100
	s_cbranch_scc1 .Lsgs_9
	s_sleep 3
; #define PG8_LAS __attribute__((address_space(3)))
;     ...
;         for (int t = 0; t < nt; ++t) {
;             asm volatile("s_waitcnt vmcnt(8)" ::: "memory"); __builtin_amdgcn_s_barrier();
;             { const int tn = (t + 3 < nt) ? t + 3 : t + 3 - nt; GS_STAGE((t + 3) & 3, cA + (size_t)tn * 128, cB + (size_t)tn * 128); }
;             const int so = (t & 3) * 32768;
;             bf16x8 At[4][2], Bf[2][2];
; #pragma unroll
;             for (int m = 0; m < 4; ++m)
; #pragma unroll
;                 for (int k = 0; k < 2; ++k) At[m][k] = *(const PG8_LAS bf16x8*)(lds + so + aoff + m * 2048 + k * 1024);
; #pragma unroll
;             for (int n = 0; n < 2; ++n)
; #pragma unroll
;                 for (int k = 0; k < 2; ++k) Bf[n][k] = *(const PG8_LAS bf16x8*)(lds + so + 16384 + boff + n * 2048 + k * 1024);
;             asm volatile("s_waitcnt lgkmcnt(0)" ::: "memory"); __builtin_amdgcn_sched_barrier(0);
; #pragma unroll
;             for (int m = 0; m < 4; ++m)
; #pragma unroll
;                 for (int n = 0; n < 2; ++n)
; #pragma unroll
;                     for (int k = 0; k < 2; ++k) acc[m][n] = __builtin_amdgcn_mfma_f32_16x16x32_bf16(Bf[n][k], At[m][k], acc[m][n], 0, 0, 0);
;         }
.Lsgs_9:
	global_load_lds_dwordx4 v[40:41], off
	v_lshl_add_u64 v[40:41], v[20:21], 0, s[42:43]
	s_mov_b32 m0, s72
	s_waitcnt lgkmcnt(0)
	v_mfma_f32_16x16x32_bf16 v[82:85], v[118:121], v[86:89], v[82:85]
	global_load_lds_dwordx4 v[40:41], off
	v_lshl_add_u64 v[40:41], v[18:19], 0, s[42:43]
	s_mov_b32 m0, s73
	v_mfma_f32_16x16x32_bf16 v[24:27], v[136:139], v[86:89], v[24:27]
	global_load_lds_dwordx4 v[40:41], off
	v_lshl_add_u64 v[40:41], v[16:17], 0, s[42:43]
	s_mov_b32 m0, s74
	v_mfma_f32_16x16x32_bf16 v[28:31], v[118:121], v[94:97], v[28:31]
	global_load_lds_dwordx4 v[40:41], off
	v_mfma_f32_16x16x32_bf16 v[36:39], v[136:139], v[94:97], v[36:39]
	v_mfma_f32_16x16x32_bf16 v[66:69], v[118:121], v[102:105], v[66:69]
	v_mfma_f32_16x16x32_bf16 v[70:73], v[136:139], v[102:105], v[70:73]
	v_mfma_f32_16x16x32_bf16 v[74:77], v[118:121], v[110:113], v[74:77]
	v_mfma_f32_16x16x32_bf16 v[82:85], v[132:135], v[90:93], v[82:85]
	v_mfma_f32_16x16x32_bf16 v[24:27], v[140:143], v[90:93], v[24:27]
	v_mfma_f32_16x16x32_bf16 v[28:31], v[132:135], v[98:101], v[28:31]
	v_mfma_f32_16x16x32_bf16 v[36:39], v[140:143], v[98:101], v[36:39]
	ds_read_b128 v[86:89], v52
	ds_read_b128 v[90:93], v53
	ds_read_b128 v[94:97], v54
	ds_read_b128 v[98:101], v55
	v_mfma_f32_16x16x32_bf16 v[66:69], v[132:135], v[106:109], v[66:69]
	v_mfma_f32_16x16x32_bf16 v[70:73], v[140:143], v[106:109], v[70:73]
	ds_read_b128 v[102:105], v56
	ds_read_b128 v[106:109], v57
	ds_read_b128 v[118:121], v58
	ds_read_b128 v[122:125], v59
	v_mfma_f32_16x16x32_bf16 v[74:77], v[132:135], v[114:117], v[74:77]
	v_mfma_f32_16x16x32_bf16 v[78:81], v[136:139], v[110:113], v[78:81]
	ds_read_b128 v[110:113], v63
	ds_read_b128 v[132:135], v63 offset:1024
	ds_read_b128 v[136:139], v63 offset:2048
	ds_read_b128 v[144:147], v63 offset:3072
	s_waitcnt lgkmcnt(0)
	v_mfma_f32_16x16x32_bf16 v[78:81], v[140:143], v[114:117], v[78:81]
	s_mov_b32 m0, s75
	v_lshl_add_u64 v[40:41], v[22:23], 0, s[44:45]
	s_waitcnt vmcnt(8)
	s_barrier
	v_readfirstlane_b32 s98, v183
	s_cmpk_ge_u32 s98, 0x100
	s_cbranch_scc1 .Lsgs_10
	s_sleep 3
.Lsgs_10:
	global_load_lds_dwordx4 v[40:41], off
	v_lshl_add_u64 v[40:41], v[20:21], 0, s[44:45]
	s_mov_b32 m0, s76
	s_waitcnt lgkmcnt(0)
	v_mfma_f32_16x16x32_bf16 v[82:85], v[110:113], v[86:89], v[82:85]
	global_load_lds_dwordx4 v[40:41], off
	v_lshl_add_u64 v[40:41], v[18:19], 0, s[44:45]
	s_mov_b32 m0, s77
	v_mfma_f32_16x16x32_bf16 v[24:27], v[136:139], v[86:89], v[24:27]
	global_load_lds_dwordx4 v[40:41], off
	v_lshl_add_u64 v[40:41], v[16:17], 0, s[44:45]
	s_mov_b32 m0, s78
	v_mfma_f32_16x16x32_bf16 v[28:31], v[110:113], v[94:97], v[28:31]
	global_load_lds_dwordx4 v[40:41], off
	v_mfma_f32_16x16x32_bf16 v[36:39], v[136:139], v[94:97], v[36:39]
	v_mfma_f32_16x16x32_bf16 v[66:69], v[110:113], v[102:105], v[66:69]
	v_mfma_f32_16x16x32_bf16 v[70:73], v[136:139], v[102:105], v[70:73]
	v_mfma_f32_16x16x32_bf16 v[74:77], v[110:113], v[118:121], v[74:77]
	v_mfma_f32_16x16x32_bf16 v[82:85], v[132:135], v[90:93], v[82:85]
	v_mfma_f32_16x16x32_bf16 v[24:27], v[144:147], v[90:93], v[24:27]
	v_mfma_f32_16x16x32_bf16 v[28:31], v[132:135], v[98:101], v[28:31]
	v_mfma_f32_16x16x32_bf16 v[36:39], v[144:147], v[98:101], v[36:39]
	ds_read_b128 v[86:89], v43
	ds_read_b128 v[90:93], v43 offset:1024
	ds_read_b128 v[94:97], v43 offset:2048
	ds_read_b128 v[98:101], v43 offset:3072
	v_mfma_f32_16x16x32_bf16 v[66:69], v[132:135], v[106:109], v[66:69]
	v_mfma_f32_16x16x32_bf16 v[70:73], v[144:147], v[106:109], v[70:73]
	ds_read_b128 v[102:105], v43 offset:4096
	ds_read_b128 v[106:109], v43 offset:5120
	ds_read_b128 v[110:113], v43 offset:6144
	ds_read_b128 v[114:117], v43 offset:7168
	v_mfma_f32_16x16x32_bf16 v[74:77], v[132:135], v[122:125], v[74:77]
	v_mfma_f32_16x16x32_bf16 v[78:81], v[136:139], v[118:121], v[78:81]
	ds_read_b128 v[118:121], v61 offset:16384
	ds_read_b128 v[132:135], v61 offset:17408
	ds_read_b128 v[136:139], v61 offset:18432
	ds_read_b128 v[140:143], v61 offset:19456
	s_waitcnt lgkmcnt(0)
	v_mfma_f32_16x16x32_bf16 v[78:81], v[144:147], v[122:125], v[78:81]
	s_mov_b32 m0, s57
	s_waitcnt vmcnt(8)
	s_barrier
	v_readfirstlane_b32 s98, v183
	s_cmpk_ge_u32 s98, 0x100
	s_cbranch_scc1 .Lsgs_11
	s_sleep 3
.Lsgs_11:
	global_load_lds_dwordx4 v[22:23], off
	s_mov_b32 m0, s59
	s_waitcnt lgkmcnt(0)
	v_mfma_f32_16x16x32_bf16 v[82:85], v[118:121], v[86:89], v[82:85]
	global_load_lds_dwordx4 v[20:21], off
	s_mov_b32 m0, s60
	v_mfma_f32_16x16x32_bf16 v[24:27], v[136:139], v[86:89], v[24:27]
	global_load_lds_dwordx4 v[18:19], off
	s_mov_b32 m0, s62
	v_mfma_f32_16x16x32_bf16 v[28:31], v[118:121], v[94:97], v[28:31]
	global_load_lds_dwordx4 v[16:17], off
	v_mfma_f32_16x16x32_bf16 v[36:39], v[136:139], v[94:97], v[36:39]
	v_mfma_f32_16x16x32_bf16 v[66:69], v[118:121], v[102:105], v[66:69]
	v_mfma_f32_16x16x32_bf16 v[20:23], v[136:139], v[102:105], v[70:73]
	v_mfma_f32_16x16x32_bf16 v[70:73], v[118:121], v[110:113], v[74:77]
	v_mfma_f32_16x16x32_bf16 v[82:85], v[132:135], v[90:93], v[82:85]
	v_mfma_f32_16x16x32_bf16 v[24:27], v[140:143], v[90:93], v[24:27]
	s_nop 0
	ds_read_b128 v[74:77], v43 offset:32768
	ds_read_b128 v[86:89], v43 offset:33792
	ds_read_b128 v[90:93], v43 offset:34816
	ds_read_b128 v[94:97], v43 offset:35840
	v_mfma_f32_16x16x32_bf16 v[28:31], v[132:135], v[98:101], v[28:31]
	v_mfma_f32_16x16x32_bf16 v[36:39], v[140:143], v[98:101], v[36:39]
	v_mfma_f32_16x16x32_bf16 v[66:69], v[132:135], v[106:109], v[66:69]
	v_mfma_f32_16x16x32_bf16 v[18:21], v[140:143], v[106:109], v[20:23]
	ds_read_b128 v[98:101], v43 offset:36864
	ds_read_b128 v[102:105], v43 offset:37888
	ds_read_b128 v[106:109], v43 offset:38912
	ds_read_b128 v[118:121], v43 offset:39936
	v_mfma_f32_16x16x32_bf16 v[70:73], v[132:135], v[114:117], v[70:73]
	v_mfma_f32_16x16x32_bf16 v[78:81], v[136:139], v[110:113], v[78:81]
	ds_read_b128 v[110:113], v61 offset:49152
	ds_read_b128 v[122:125], v61 offset:50176
	ds_read_b128 v[132:135], v61 offset:51200
	ds_read_b128 v[136:139], v61 offset:52224
	s_waitcnt lgkmcnt(0)
	v_mfma_f32_16x16x32_bf16 v[78:81], v[140:143], v[114:117], v[78:81]
	s_mov_b32 m0, s64
	s_waitcnt vmcnt(8)
	s_barrier
	v_readfirstlane_b32 s98, v183
	s_cmpk_ge_u32 s98, 0x100
	s_cbranch_scc1 .Lsgs_12
	s_sleep 3
; #define PG8_LAS __attribute__((address_space(3)))
;     ...
;         for (int t = 0; t < nt; ++t) {
;             asm volatile("s_waitcnt vmcnt(8)" ::: "memory"); __builtin_amdgcn_s_barrier();
;             { const int tn = (t + 3 < nt) ? t + 3 : t + 3 - nt; GS_STAGE((t + 3) & 3, cA + (size_t)tn * 128, cB + (size_t)tn * 128); }
;             const int so = (t & 3) * 32768;
;             bf16x8 At[4][2], Bf[2][2];
; #pragma unroll
;             for (int m = 0; m < 4; ++m)
; #pragma unroll
;                 for (int k = 0; k < 2; ++k) At[m][k] = *(const PG8_LAS bf16x8*)(lds + so + aoff + m * 2048 + k * 1024);
; #pragma unroll
;             for (int n = 0; n < 2; ++n)
; #pragma unroll
;                 for (int k = 0; k < 2; ++k) Bf[n][k] = *(const PG8_LAS bf16x8*)(lds + so + 16384 + boff + n * 2048 + k * 1024);
;             asm volatile("s_waitcnt lgkmcnt(0)" ::: "memory"); __builtin_amdgcn_sched_barrier(0);
; #pragma unroll
;             for (int m = 0; m < 4; ++m)
; #pragma unroll
;                 for (int n = 0; n < 2; ++n)
; #pragma unroll
;                     for (int k = 0; k < 2; ++k) acc[m][n] = __builtin_amdgcn_mfma_f32_16x16x32_bf16(Bf[n][k], At[m][k], acc[m][n], 0, 0, 0);
;         }
;         asm volatile("s_waitcnt vmcnt(0)" ::: "memory"); __builtin_amdgcn_s_barrier();
;         if (KS > 1) {
;             typedef unsigned long long u64;
;             const int unit = pn * nMq + pm; u64* part = (u64*)scr + (size_t)unit * KS * 16 * 512 + tid;
; #pragma unroll
;             for (int j = 0; j < 16; ++j) { const f32x4 v = acc[j >> 2][(j >> 1) & 1]; const float lo = (j & 1) ? v[2] : v[0], hi2 = (j & 1) ? v[3] : v[1];
;                 __hip_atomic_store(part + (size_t)(split * 16 + j) * 512, ((u64)__float_as_uint(hi2) << 32) | (u64)__float_as_uint(lo), __ATOMIC_RELAXED, __HIP_MEMORY_SCOPE_AGENT); }
;             asm volatile("s_waitcnt vmcnt(0)" ::: "memory"); __syncthreads();
;             if (tid == 0) { const unsigned old = __hip_atomic_fetch_add(cnt + unit, 1u, __ATOMIC_RELAXED, __HIP_MEMORY_SCOPE_AGENT); *(PG8_LAS unsigned*)(lds + 131072) = old; }
.Lsgs_12:
	global_load_lds_dwordx4 v[14:15], off
	s_mov_b32 m0, s66
	s_waitcnt lgkmcnt(0)
	v_mfma_f32_16x16x32_bf16 v[18:21], v[132:135], v[98:101], v[18:21]
	global_load_lds_dwordx4 v[12:13], off
	s_mov_b32 m0, s68
	v_mfma_f32_16x16x32_bf16 v[82:85], v[110:113], v[74:77], v[82:85]
	global_load_lds_dwordx4 v[10:11], off
	s_mov_b32 m0, s70
	v_mfma_f32_16x16x32_bf16 v[22:25], v[132:135], v[74:77], v[24:27]
	global_load_lds_dwordx4 v[8:9], off
	v_mfma_f32_16x16x32_bf16 v[26:29], v[110:113], v[90:93], v[28:31]
	v_mfma_f32_16x16x32_bf16 v[36:39], v[132:135], v[90:93], v[36:39]
	v_mfma_f32_16x16x32_bf16 v[66:69], v[110:113], v[98:101], v[66:69]
	v_mfma_f32_16x16x32_bf16 v[10:13], v[136:139], v[102:105], v[18:21]
	v_mfma_f32_16x16x32_bf16 v[18:21], v[110:113], v[106:109], v[70:73]
	v_mfma_f32_16x16x32_bf16 v[82:85], v[122:125], v[86:89], v[82:85]
	v_mfma_f32_16x16x32_bf16 v[22:25], v[136:139], v[86:89], v[22:25]
	v_mfma_f32_16x16x32_bf16 v[26:29], v[122:125], v[94:97], v[26:29]
	v_mfma_f32_16x16x32_bf16 v[36:39], v[136:139], v[94:97], v[36:39]
	v_mfma_f32_16x16x32_bf16 v[14:17], v[122:125], v[102:105], v[66:69]
	s_nop 2
	ds_read_b128 v[66:69], v44
	ds_read_b128 v[70:73], v45
	ds_read_b128 v[74:77], v46
	ds_read_b128 v[86:89], v47
	ds_read_b128 v[90:93], v48
	ds_read_b128 v[94:97], v49
	ds_read_b128 v[98:101], v50
	ds_read_b128 v[102:105], v51
	v_mfma_f32_16x16x32_bf16 v[18:21], v[122:125], v[118:121], v[18:21]
	v_mfma_f32_16x16x32_bf16 v[78:81], v[132:135], v[106:109], v[78:81]
	ds_read_b128 v[106:109], v62
	ds_read_b128 v[110:113], v62 offset:1024
	ds_read_b128 v[114:117], v62 offset:2048
	ds_read_b128 v[122:125], v62 offset:3072
	s_waitcnt lgkmcnt(0)
	v_mfma_f32_16x16x32_bf16 v[78:81], v[136:139], v[118:121], v[78:81]
	s_mov_b32 m0, s71
	s_waitcnt vmcnt(8)
	s_barrier
	v_readfirstlane_b32 s98, v183
	s_cmpk_ge_u32 s98, 0x100
	s_cbranch_scc1 .Lsgs_13
	s_sleep 3
.Lsgs_13:
	global_load_lds_dwordx4 v[6:7], off
	s_mov_b32 m0, s72
	s_waitcnt lgkmcnt(0)
	v_mfma_f32_16x16x32_bf16 v[82:85], v[106:109], v[66:69], v[82:85]
	global_load_lds_dwordx4 v[4:5], off
	s_mov_b32 m0, s73
	v_mfma_f32_16x16x32_bf16 v[22:25], v[114:117], v[66:69], v[22:25]
	global_load_lds_dwordx4 v[2:3], off
	s_mov_b32 m0, s74
	v_mfma_f32_16x16x32_bf16 v[26:29], v[106:109], v[74:77], v[26:29]
	global_load_lds_dwordx4 v[0:1], off
	v_mfma_f32_16x16x32_bf16 v[36:39], v[114:117], v[74:77], v[36:39]
	v_mfma_f32_16x16x32_bf16 v[14:17], v[106:109], v[90:93], v[14:17]
	v_mfma_f32_16x16x32_bf16 v[4:7], v[114:117], v[90:93], v[10:13]
	v_mfma_f32_16x16x32_bf16 v[0:3], v[106:109], v[98:101], v[18:21]
	v_mfma_f32_16x16x32_bf16 v[82:85], v[110:113], v[70:73], v[82:85]
	v_mfma_f32_16x16x32_bf16 v[22:25], v[122:125], v[70:73], v[22:25]
	v_mfma_f32_16x16x32_bf16 v[26:29], v[110:113], v[86:89], v[26:29]
	v_mfma_f32_16x16x32_bf16 v[36:39], v[122:125], v[86:89], v[36:39]
	v_mfma_f32_16x16x32_bf16 v[66:69], v[110:113], v[94:97], v[14:17]
	v_mfma_f32_16x16x32_bf16 v[70:73], v[122:125], v[94:97], v[4:7]
	s_nop 2
	ds_read_b128 v[4:7], v52
	ds_read_b128 v[8:11], v53
	ds_read_b128 v[12:15], v54
	ds_read_b128 v[16:19], v55
	ds_read_b128 v[86:89], v56
	ds_read_b128 v[90:93], v57
	ds_read_b128 v[94:97], v58
	ds_read_b128 v[106:109], v59
	v_mfma_f32_16x16x32_bf16 v[74:77], v[110:113], v[102:105], v[0:3]
	v_mfma_f32_16x16x32_bf16 v[0:3], v[114:117], v[98:101], v[78:81]
	s_nop 2
	ds_read_b128 v[78:81], v63
	ds_read_b128 v[98:101], v63 offset:1024
	ds_read_b128 v[110:113], v63 offset:2048
	ds_read_b128 v[114:117], v63 offset:3072
	s_waitcnt lgkmcnt(0)
	v_mfma_f32_16x16x32_bf16 v[102:105], v[122:125], v[102:105], v[0:3]
	s_waitcnt lgkmcnt(0)
	v_mfma_f32_16x16x32_bf16 v[0:3], v[78:81], v[4:7], v[82:85]
	s_lshl_b32 s12, s80, 2
	s_or_b32 s82, s12, s3
	s_lshl_b32 s12, s82, 18
	v_mfma_f32_16x16x32_bf16 v[4:7], v[110:113], v[4:7], v[22:25]
	s_waitcnt vmcnt(0)
	s_barrier
	v_mfma_f32_16x16x32_bf16 v[0:3], v[98:101], v[8:11], v[0:3]
	v_mfma_f32_16x16x32_bf16 v[4:7], v[114:117], v[8:11], v[4:7]
	v_mfma_f32_16x16x32_bf16 v[8:11], v[78:81], v[12:15], v[26:29]
	v_mfma_f32_16x16x32_bf16 v[12:15], v[110:113], v[12:15], v[36:39]
	s_nop 2
	v_lshl_add_u64 v[36:37], v[34:35], 0, s[12:13]
	s_lshl_b32 s12, s2, 16
	v_lshl_add_u64 v[38:39], v[36:37], 0, s[12:13]
	v_add_co_u32_e32 v20, vcc, s56, v38
	v_mfma_f32_16x16x32_bf16 v[8:11], v[98:101], v[16:19], v[8:11]
	s_nop 0
	v_addc_co_u32_e32 v21, vcc, 0, v39, vcc
	global_store_dwordx2 v[38:39], v[0:1], off sc1
	v_mfma_f32_16x16x32_bf16 v[12:15], v[114:117], v[16:19], v[12:15]
	global_store_dwordx2 v[20:21], v[2:3], off offset:-4096 sc1
	global_store_dwordx2 v[20:21], v[4:5], off sc1
	v_add_co_u32_e32 v20, vcc, s58, v38
	v_mfma_f32_16x16x32_bf16 v[16:19], v[78:81], v[86:89], v[66:69]
	s_nop 0
	v_addc_co_u32_e32 v21, vcc, 0, v39, vcc
	v_add_co_u32_e32 v24, vcc, s61, v38
	v_mfma_f32_16x16x32_bf16 v[16:19], v[98:101], v[90:93], v[16:19]
	global_store_dwordx2 v[20:21], v[6:7], off offset:-4096 sc1
	global_store_dwordx2 v[20:21], v[8:9], off sc1
	v_addc_co_u32_e32 v25, vcc, 0, v39, vcc
	v_mfma_f32_16x16x32_bf16 v[20:23], v[110:113], v[86:89], v[70:73]
	global_store_dwordx2 v[24:25], v[10:11], off offset:-4096 sc1
	global_store_dwordx2 v[24:25], v[12:13], off sc1
	v_add_co_u32_e32 v24, vcc, s63, v38
	v_mfma_f32_16x16x32_bf16 v[20:23], v[114:117], v[90:93], v[20:23]
	s_nop 0
	v_addc_co_u32_e32 v25, vcc, 0, v39, vcc
	global_store_dwordx2 v[24:25], v[14:15], off offset:-4096 sc1
	global_store_dwordx2 v[24:25], v[16:17], off sc1
	v_mfma_f32_16x16x32_bf16 v[24:27], v[78:81], v[94:97], v[74:77]
	v_add_co_u32_e32 v28, vcc, s67, v38
	s_nop 1
	v_addc_co_u32_e32 v29, vcc, 0, v39, vcc
	global_store_dwordx2 v[28:29], v[18:19], off offset:-4096 sc1
	global_store_dwordx2 v[28:29], v[20:21], off sc1
	v_mfma_f32_16x16x32_bf16 v[24:27], v[98:101], v[106:109], v[24:27]
	v_add_co_u32_e32 v40, vcc, s65, v38
	v_mfma_f32_16x16x32_bf16 v[28:31], v[110:113], v[94:97], v[102:105]
	s_nop 0
	v_addc_co_u32_e32 v41, vcc, 0, v39, vcc
	global_store_dwordx2 v[40:41], v[22:23], off offset:-4096 sc1
	s_nop 2
	global_store_dwordx2 v[40:41], v[24:25], off sc1
	v_add_co_u32_e32 v40, vcc, s69, v38
	v_mfma_f32_16x16x32_bf16 v[28:31], v[114:117], v[106:109], v[28:31]
	s_nop 0
	v_addc_co_u32_e32 v41, vcc, 0, v39, vcc
	v_add_co_u32_e32 v38, vcc, 0xf000, v38
	global_store_dwordx2 v[40:41], v[26:27], off offset:-4096 sc1
	s_nop 3
	global_store_dwordx2 v[40:41], v[28:29], off sc1
	v_addc_co_u32_e32 v39, vcc, 0, v39, vcc
	global_store_dwordx2 v[38:39], v[30:31], off sc1
	s_waitcnt vmcnt(0)
	s_waitcnt vmcnt(0)
	s_barrier
	s_mov_b64 s[2:3], exec
	v_readlane_b32 s46, v253, 14
	v_readlane_b32 s47, v253, 15
	s_and_b64 s[46:47], s[2:3], s[46:47]
	s_mov_b64 exec, s[46:47]
	s_cbranch_execz .LBB0_1390
	s_mov_b64 s[48:49], exec
	v_mbcnt_lo_u32_b32 v32, s48, 0
	v_mbcnt_hi_u32_b32 v32, s49, v32
	v_cmp_eq_u32_e32 vcc, 0, v32
	s_and_saveexec_b64 s[46:47], vcc
	s_cbranch_execz .LBB0_1389
	s_lshl_b32 s12, s82, 2
	s_bcnt1_i32_b64 s48, s[48:49]
	v_mov_b32_e32 v38, s12
	v_mov_b32_e32 v39, s48
	global_atomic_add v38, v38, v39, s[10:11] sc0
